# GEMM phases: in the last K-pair of a workgroup's last tile the next-tile LDS-DMA pieces are issued with EXEC=0 (no re-read of the current tile during the final epilogue); that iteration's waits are vm
# baseline (speedup 1.0000x reference)
.LBB0_149:
	s_add_i32 s93, s9, 1
	s_mul_i32 s6, s93, s73
	s_mul_hi_u32 s7, s93, s72
	s_add_i32 s7, s7, s6
	s_mul_i32 s6, s93, s72
	s_add_u32 s38, s6, s2
	s_addc_u32 s39, s7, s3
	v_cmp_gt_i64_e32 vcc, s[38:39], v[162:163]
	v_cmp_lt_i64_e64 s[6:7], s[38:39], v[160:161]
	s_and_b64 s[98:99], s[6:7], exec
	s_cselect_b32 s100, -1, 0
	s_cbranch_vccnz .LBB0_151
	s_ashr_i32 s11, s38, 31
	s_lshr_b32 s11, s11, 29
	s_add_i32 s11, s38, s11
	s_ashr_i32 s22, s11, 3
	s_and_b32 s11, s11, -8
	s_sub_i32 s11, s38, s11
	s_cmp_lt_i32 s11, 0
	s_movk_i32 s34, 0x71
	s_cselect_b32 s34, s34, 0x70
	s_mul_i32 s11, s34, s11
	s_add_i32 s11, s11, s22
	s_mul_hi_i32 s22, s11, 0x92492493
	s_add_i32 s22, s22, s11
	s_lshr_b32 s34, s22, 31
	s_ashr_i32 s22, s22, 5
	s_add_i32 s22, s22, s34
	s_lshl_b32 s35, s22, 3
	s_sub_i32 s34, 0x80, s35
	s_min_i32 s36, s34, 8
	s_abs_i32 s34, s36
	v_cvt_f32_u32_e32 v0, s34
	s_sub_i32 s38, 0, s34
	s_mul_i32 s22, s22, 56
	s_sub_i32 s11, s11, s22
	v_rcp_iflag_f32_e32 v0, v0
	s_abs_i32 s22, s11
	s_xor_b32 s37, s11, s36
	s_ashr_i32 s37, s37, 31
	v_mul_f32_e32 v0, 0x4f7ffffe, v0
	v_cvt_u32_f32_e32 v0, v0
	s_nop 0
	v_readfirstlane_b32 s39, v0
	s_mul_i32 s38, s38, s39
	s_mul_hi_u32 s38, s39, s38
	s_add_i32 s39, s39, s38
	s_mul_hi_u32 s38, s22, s39
	s_mul_i32 s39, s38, s34
	s_sub_i32 s22, s22, s39
	s_add_i32 s40, s38, 1
	s_sub_i32 s39, s22, s34
	s_cmp_ge_u32 s22, s34
	s_cselect_b32 s38, s40, s38
	s_cselect_b32 s22, s39, s22
	s_add_i32 s39, s38, 1
	s_cmp_ge_u32 s22, s34
	s_cselect_b32 s22, s39, s38
	s_xor_b32 s22, s22, s37
	s_sub_i32 s34, s22, s37
	s_mul_i32 s22, s34, s36
	s_sub_i32 s11, s11, s22
	s_add_i32 s36, s11, s35

.LBB0_152:
	ds_read_b128 v[128:131], v192
	ds_read_b128 v[132:135], v192 offset:1024
	ds_read_b128 v[136:139], v192 offset:2048
	ds_read_b128 v[140:143], v192 offset:3072
	ds_read_b128 v[164:167], v193
	ds_read_b128 v[168:171], v193 offset:1024
	ds_read_b128 v[172:175], v193 offset:2048
	ds_read_b128 v[176:179], v193 offset:3072
	s_add_u32 s78, s70, 0xfffc0080
	s_addc_u32 s79, s71, -1
	s_cmp_eq_u32 s96, 12
	s_cselect_b32 s81, s11, s79
	s_cselect_b32 s80, s22, s78
	s_cselect_b32 s79, s35, s95
	s_cselect_b32 s78, s37, s94
	s_cselect_b32 s99, 0, -1
	s_or_b32 s99, s99, s100
	s_mov_b32 s98, s99
	v_lshl_add_u64 v[228:229], s[70:71], 0, v[156:157]
	s_add_i32 m0, s82, 0xc000
	ds_read_b128 v[196:199], v194
	ds_read_b128 v[200:203], v194 offset:1024
	ds_read_b128 v[204:207], v194 offset:2048
	ds_read_b128 v[208:211], v194 offset:3072
	ds_read_b128 v[212:215], v194 offset:4096
	ds_read_b128 v[216:219], v194 offset:5120
	ds_read_b128 v[220:223], v194 offset:6144
	ds_read_b128 v[224:227], v194 offset:7168
	global_load_lds_dwordx4 v[228:229], off
	v_lshl_add_u64 v[228:229], s[70:71], 0, v[158:159]
	s_add_i32 m0, s82, 0xe000
	s_nop 0
	global_load_lds_dwordx4 v[228:229], off
	s_waitcnt vmcnt(8)
	s_waitcnt lgkmcnt(0)
	s_barrier
	s_waitcnt lgkmcnt(0)
	v_mfma_f32_16x16x32_bf16 v[124:127], v[128:131], v[196:199], v[124:127]
	v_mfma_f32_16x16x32_bf16 v[120:123], v[136:139], v[196:199], v[120:123]
	v_mfma_f32_16x16x32_bf16 v[108:111], v[128:131], v[204:207], v[108:111]
	v_mfma_f32_16x16x32_bf16 v[104:107], v[136:139], v[204:207], v[104:107]
	v_mfma_f32_16x16x32_bf16 v[92:95], v[128:131], v[212:215], v[92:95]
	v_mfma_f32_16x16x32_bf16 v[88:91], v[136:139], v[212:215], v[88:91]
	v_mfma_f32_16x16x32_bf16 v[76:79], v[128:131], v[220:223], v[76:79]
	v_mfma_f32_16x16x32_bf16 v[72:75], v[136:139], v[220:223], v[72:75]
	v_mfma_f32_16x16x32_bf16 v[124:127], v[132:135], v[200:203], v[124:127]
	v_mfma_f32_16x16x32_bf16 v[120:123], v[140:143], v[200:203], v[120:123]
	v_mfma_f32_16x16x32_bf16 v[108:111], v[132:135], v[208:211], v[108:111]
	v_mfma_f32_16x16x32_bf16 v[104:107], v[140:143], v[208:211], v[104:107]
	v_mfma_f32_16x16x32_bf16 v[92:95], v[132:135], v[216:219], v[92:95]
	v_mfma_f32_16x16x32_bf16 v[88:91], v[140:143], v[216:219], v[88:91]
	v_mfma_f32_16x16x32_bf16 v[76:79], v[132:135], v[224:227], v[76:79]
	v_mfma_f32_16x16x32_bf16 v[72:75], v[140:143], v[224:227], v[72:75]
	v_mfma_f32_16x16x32_bf16 v[116:119], v[164:167], v[196:199], v[116:119]
	v_mfma_f32_16x16x32_bf16 v[112:115], v[172:175], v[196:199], v[112:115]
	v_mfma_f32_16x16x32_bf16 v[100:103], v[164:167], v[204:207], v[100:103]
	v_mfma_f32_16x16x32_bf16 v[96:99], v[172:175], v[204:207], v[96:99]
	v_mfma_f32_16x16x32_bf16 v[84:87], v[164:167], v[212:215], v[84:87]
	v_mfma_f32_16x16x32_bf16 v[80:83], v[172:175], v[212:215], v[80:83]
	v_mfma_f32_16x16x32_bf16 v[68:71], v[164:167], v[220:223], v[68:71]
	v_mfma_f32_16x16x32_bf16 v[64:67], v[172:175], v[220:223], v[64:67]
	v_mfma_f32_16x16x32_bf16 v[116:119], v[168:171], v[200:203], v[116:119]
	v_mfma_f32_16x16x32_bf16 v[112:115], v[176:179], v[200:203], v[112:115]
	v_mfma_f32_16x16x32_bf16 v[100:103], v[168:171], v[208:211], v[100:103]
	v_mfma_f32_16x16x32_bf16 v[96:99], v[176:179], v[208:211], v[96:99]
	v_mfma_f32_16x16x32_bf16 v[84:87], v[168:171], v[216:219], v[84:87]
	v_mfma_f32_16x16x32_bf16 v[80:83], v[176:179], v[216:219], v[80:83]
	s_setprio 3
	s_barrier
	v_mfma_f32_16x16x32_bf16 v[68:71], v[168:171], v[224:227], v[68:71]
	v_mfma_f32_16x16x32_bf16 v[64:67], v[176:179], v[224:227], v[64:67]
	s_setprio 0
	s_add_i32 s97, s90, s33
	v_lshl_add_u64 v[228:229], s[78:79], 0, v[146:147]
	s_mov_b32 m0, s97
	ds_read_b128 v[196:199], v194 offset:16384
	ds_read_b128 v[200:203], v194 offset:17408
	ds_read_b128 v[204:207], v194 offset:18432
	ds_read_b128 v[208:211], v194 offset:19456
	ds_read_b128 v[212:215], v194 offset:20480
	ds_read_b128 v[216:219], v194 offset:21504
	ds_read_b128 v[220:223], v194 offset:22528
	ds_read_b128 v[224:227], v194 offset:23552
	s_mov_b64 exec, s[98:99]
	global_load_lds_dwordx4 v[228:229], off
	s_add_i32 m0, s97, 0x2000
	s_add_u32 vcc_lo, s78, 0x40000
	v_lshl_add_u64 v[230:231], s[78:79], 0, v[150:151]
	s_addc_u32 vcc_hi, s79, 0
	s_add_i32 s97, s91, s33
	global_load_lds_dwordx4 v[230:231], off
	v_lshl_add_u64 v[232:233], vcc, 0, v[146:147]
	s_mov_b32 m0, s97
	global_load_lds_dwordx4 v[232:233], off
	v_lshl_add_u64 v[232:233], vcc, 0, v[150:151]
	s_add_i32 m0, s97, 0x2000
	s_nop 0
	global_load_lds_dwordx4 v[232:233], off
	s_mov_b64 exec, -1
	s_cmp_lg_u32 s99, 0
	s_cbranch_scc1 .Lng_0_1
	s_waitcnt vmcnt(0)
.Lng_0_1:
	s_waitcnt vmcnt(6)
	s_waitcnt lgkmcnt(0)
	s_barrier
	s_waitcnt lgkmcnt(0)
	v_mfma_f32_16x16x32_bf16 v[60:63], v[128:131], v[196:199], v[60:63]
	v_mfma_f32_16x16x32_bf16 v[56:59], v[136:139], v[196:199], v[56:59]
	v_mfma_f32_16x16x32_bf16 v[44:47], v[128:131], v[204:207], v[44:47]
	v_mfma_f32_16x16x32_bf16 v[40:43], v[136:139], v[204:207], v[40:43]
	v_mfma_f32_16x16x32_bf16 v[28:31], v[128:131], v[212:215], v[28:31]
	v_mfma_f32_16x16x32_bf16 v[24:27], v[136:139], v[212:215], v[24:27]
	v_mfma_f32_16x16x32_bf16 v[12:15], v[128:131], v[220:223], v[12:15]
	v_mfma_f32_16x16x32_bf16 v[8:11], v[136:139], v[220:223], v[8:11]
	v_mfma_f32_16x16x32_bf16 v[60:63], v[132:135], v[200:203], v[60:63]
	v_mfma_f32_16x16x32_bf16 v[56:59], v[140:143], v[200:203], v[56:59]
	v_mfma_f32_16x16x32_bf16 v[44:47], v[132:135], v[208:211], v[44:47]
	v_mfma_f32_16x16x32_bf16 v[40:43], v[140:143], v[208:211], v[40:43]
	v_mfma_f32_16x16x32_bf16 v[28:31], v[132:135], v[216:219], v[28:31]
	v_mfma_f32_16x16x32_bf16 v[24:27], v[140:143], v[216:219], v[24:27]
	v_mfma_f32_16x16x32_bf16 v[12:15], v[132:135], v[224:227], v[12:15]
	v_mfma_f32_16x16x32_bf16 v[8:11], v[140:143], v[224:227], v[8:11]
	v_mfma_f32_16x16x32_bf16 v[52:55], v[164:167], v[196:199], v[52:55]
	v_mfma_f32_16x16x32_bf16 v[48:51], v[172:175], v[196:199], v[48:51]
	v_mfma_f32_16x16x32_bf16 v[36:39], v[164:167], v[204:207], v[36:39]
	v_mfma_f32_16x16x32_bf16 v[32:35], v[172:175], v[204:207], v[32:35]
	v_mfma_f32_16x16x32_bf16 v[20:23], v[164:167], v[212:215], v[20:23]
	v_mfma_f32_16x16x32_bf16 v[16:19], v[172:175], v[212:215], v[16:19]
	v_mfma_f32_16x16x32_bf16 v[4:7], v[164:167], v[220:223], v[4:7]
	v_mfma_f32_16x16x32_bf16 v[0:3], v[172:175], v[220:223], v[0:3]
	v_mfma_f32_16x16x32_bf16 v[52:55], v[168:171], v[200:203], v[52:55]
	v_mfma_f32_16x16x32_bf16 v[48:51], v[176:179], v[200:203], v[48:51]
	v_mfma_f32_16x16x32_bf16 v[36:39], v[168:171], v[208:211], v[36:39]
	v_mfma_f32_16x16x32_bf16 v[32:35], v[176:179], v[208:211], v[32:35]
	v_mfma_f32_16x16x32_bf16 v[20:23], v[168:171], v[216:219], v[20:23]
	v_mfma_f32_16x16x32_bf16 v[16:19], v[176:179], v[216:219], v[16:19]
	s_setprio 3
	s_barrier
	v_mfma_f32_16x16x32_bf16 v[4:7], v[168:171], v[224:227], v[4:7]
	v_mfma_f32_16x16x32_bf16 v[0:3], v[176:179], v[224:227], v[0:3]
	s_setprio 0
	s_add_i32 s97, 0, 0x18000
	s_add_i32 vcc_lo, 0, 0x1c000
	v_add_u32_e32 v140, s97, v180
	v_add_u32_e32 v152, vcc_lo, v180
	ds_read_b128 v[128:131], v140
	ds_read_b128 v[132:135], v140 offset:1024
	ds_read_b128 v[136:139], v140 offset:2048
	ds_read_b128 v[140:143], v140 offset:3072
	ds_read_b128 v[164:167], v152
	ds_read_b128 v[168:171], v152 offset:1024
	ds_read_b128 v[172:175], v152 offset:2048
	ds_read_b128 v[176:179], v152 offset:3072
	v_lshl_add_u64 v[232:233], s[80:81], 0, v[144:145]
	s_mov_b32 m0, s82
	v_lshl_add_u64 v[234:235], s[80:81], 0, v[148:149]
	s_mov_b64 exec, s[98:99]
	global_load_lds_dwordx4 v[232:233], off
	s_mov_b32 m0, s83
	s_nop 0
	global_load_lds_dwordx4 v[234:235], off
	s_mov_b64 exec, -1
	s_add_u32 s80, s80, 0x40000
	s_addc_u32 s81, s81, 0
	s_mov_b32 m0, s84
	v_lshl_add_u64 v[236:237], s[80:81], 0, v[144:145]
	ds_read_b128 v[196:199], v194 offset:32768
	ds_read_b128 v[200:203], v194 offset:33792
	ds_read_b128 v[204:207], v194 offset:34816
	ds_read_b128 v[208:211], v194 offset:35840
	ds_read_b128 v[212:215], v194 offset:36864
	ds_read_b128 v[216:219], v194 offset:37888
	ds_read_b128 v[220:223], v194 offset:38912
	ds_read_b128 v[224:227], v194 offset:39936
	s_mov_b64 exec, s[98:99]
	global_load_lds_dwordx4 v[236:237], off
	v_lshl_add_u64 v[236:237], s[80:81], 0, v[148:149]
	s_mov_b32 m0, s85
	s_nop 0
	global_load_lds_dwordx4 v[236:237], off
	s_mov_b64 exec, -1
	s_cmp_lg_u32 s99, 0
	s_cbranch_scc1 .Lng_0_2
	s_waitcnt vmcnt(0)
.Lng_0_2:
	s_waitcnt vmcnt(8)
	s_waitcnt lgkmcnt(0)
	s_barrier
	s_waitcnt lgkmcnt(0)
	v_mfma_f32_16x16x32_bf16 v[124:127], v[128:131], v[196:199], v[124:127]
	v_mfma_f32_16x16x32_bf16 v[120:123], v[136:139], v[196:199], v[120:123]
	v_mfma_f32_16x16x32_bf16 v[108:111], v[128:131], v[204:207], v[108:111]
	v_mfma_f32_16x16x32_bf16 v[104:107], v[136:139], v[204:207], v[104:107]
	v_mfma_f32_16x16x32_bf16 v[92:95], v[128:131], v[212:215], v[92:95]
	v_mfma_f32_16x16x32_bf16 v[88:91], v[136:139], v[212:215], v[88:91]
	v_mfma_f32_16x16x32_bf16 v[76:79], v[128:131], v[220:223], v[76:79]
	v_mfma_f32_16x16x32_bf16 v[72:75], v[136:139], v[220:223], v[72:75]
	v_mfma_f32_16x16x32_bf16 v[124:127], v[132:135], v[200:203], v[124:127]
	v_mfma_f32_16x16x32_bf16 v[120:123], v[140:143], v[200:203], v[120:123]
	v_mfma_f32_16x16x32_bf16 v[108:111], v[132:135], v[208:211], v[108:111]
	v_mfma_f32_16x16x32_bf16 v[104:107], v[140:143], v[208:211], v[104:107]
	v_mfma_f32_16x16x32_bf16 v[92:95], v[132:135], v[216:219], v[92:95]
	v_mfma_f32_16x16x32_bf16 v[88:91], v[140:143], v[216:219], v[88:91]
	v_mfma_f32_16x16x32_bf16 v[76:79], v[132:135], v[224:227], v[76:79]
	v_mfma_f32_16x16x32_bf16 v[72:75], v[140:143], v[224:227], v[72:75]
	v_mfma_f32_16x16x32_bf16 v[116:119], v[164:167], v[196:199], v[116:119]
	v_mfma_f32_16x16x32_bf16 v[112:115], v[172:175], v[196:199], v[112:115]
	v_mfma_f32_16x16x32_bf16 v[100:103], v[164:167], v[204:207], v[100:103]
	v_mfma_f32_16x16x32_bf16 v[96:99], v[172:175], v[204:207], v[96:99]
	v_mfma_f32_16x16x32_bf16 v[84:87], v[164:167], v[212:215], v[84:87]
	v_mfma_f32_16x16x32_bf16 v[80:83], v[172:175], v[212:215], v[80:83]
	v_mfma_f32_16x16x32_bf16 v[68:71], v[164:167], v[220:223], v[68:71]
	v_mfma_f32_16x16x32_bf16 v[64:67], v[172:175], v[220:223], v[64:67]
	v_mfma_f32_16x16x32_bf16 v[116:119], v[168:171], v[200:203], v[116:119]
	v_mfma_f32_16x16x32_bf16 v[112:115], v[176:179], v[200:203], v[112:115]
	v_mfma_f32_16x16x32_bf16 v[100:103], v[168:171], v[208:211], v[100:103]
	v_mfma_f32_16x16x32_bf16 v[96:99], v[176:179], v[208:211], v[96:99]
	v_mfma_f32_16x16x32_bf16 v[84:87], v[168:171], v[216:219], v[84:87]
	v_mfma_f32_16x16x32_bf16 v[80:83], v[176:179], v[216:219], v[80:83]
	s_setprio 3
	s_barrier
	v_mfma_f32_16x16x32_bf16 v[68:71], v[168:171], v[224:227], v[68:71]
	v_mfma_f32_16x16x32_bf16 v[64:67], v[176:179], v[224:227], v[64:67]
	s_setprio 0
	s_add_i32 s80, s97, s33
	v_lshl_add_u64 v[228:229], v[228:229], 0, s[26:27]
	s_mov_b32 m0, s80
	ds_read_b128 v[196:199], v194 offset:49152
	ds_read_b128 v[200:203], v194 offset:50176
	ds_read_b128 v[204:207], v194 offset:51200
	ds_read_b128 v[208:211], v194 offset:52224
	ds_read_b128 v[212:215], v194 offset:53248
	ds_read_b128 v[216:219], v194 offset:54272
	ds_read_b128 v[220:223], v194 offset:55296
	ds_read_b128 v[224:227], v194 offset:56320
	s_mov_b64 exec, s[98:99]
	global_load_lds_dwordx4 v[228:229], off
	s_add_i32 m0, s80, 0x2000
	s_add_u32 s78, s78, 0x40080
	v_lshl_add_u64 v[228:229], v[230:231], 0, s[26:27]
	s_addc_u32 s79, s79, 0
	s_add_i32 s80, vcc_lo, s33
	global_load_lds_dwordx4 v[228:229], off
	v_lshl_add_u64 v[228:229], s[78:79], 0, v[146:147]
	s_mov_b32 m0, s80
	s_nop 0
	global_load_lds_dwordx4 v[228:229], off
	v_lshl_add_u64 v[228:229], s[78:79], 0, v[150:151]
	s_add_i32 m0, s80, 0x2000
	s_nop 0
	global_load_lds_dwordx4 v[228:229], off
	s_mov_b64 exec, -1
	s_cmp_lg_u32 s99, 0
	s_cbranch_scc1 .Lng_0_3
	s_waitcnt vmcnt(0)
.Lng_0_3:
	s_waitcnt vmcnt(6)
	s_waitcnt lgkmcnt(0)
	s_barrier
	s_waitcnt lgkmcnt(0)
	v_mfma_f32_16x16x32_bf16 v[60:63], v[128:131], v[196:199], v[60:63]
	v_mfma_f32_16x16x32_bf16 v[56:59], v[136:139], v[196:199], v[56:59]
	v_mfma_f32_16x16x32_bf16 v[44:47], v[128:131], v[204:207], v[44:47]
	v_mfma_f32_16x16x32_bf16 v[40:43], v[136:139], v[204:207], v[40:43]
	v_mfma_f32_16x16x32_bf16 v[28:31], v[128:131], v[212:215], v[28:31]
	v_mfma_f32_16x16x32_bf16 v[24:27], v[136:139], v[212:215], v[24:27]
	v_mfma_f32_16x16x32_bf16 v[12:15], v[128:131], v[220:223], v[12:15]
	v_mfma_f32_16x16x32_bf16 v[8:11], v[136:139], v[220:223], v[8:11]
	v_mfma_f32_16x16x32_bf16 v[60:63], v[132:135], v[200:203], v[60:63]
	v_mfma_f32_16x16x32_bf16 v[56:59], v[140:143], v[200:203], v[56:59]
	v_mfma_f32_16x16x32_bf16 v[44:47], v[132:135], v[208:211], v[44:47]
	v_mfma_f32_16x16x32_bf16 v[40:43], v[140:143], v[208:211], v[40:43]
	v_mfma_f32_16x16x32_bf16 v[28:31], v[132:135], v[216:219], v[28:31]
	v_mfma_f32_16x16x32_bf16 v[24:27], v[140:143], v[216:219], v[24:27]
	v_mfma_f32_16x16x32_bf16 v[12:15], v[132:135], v[224:227], v[12:15]
	v_mfma_f32_16x16x32_bf16 v[8:11], v[140:143], v[224:227], v[8:11]
	v_mfma_f32_16x16x32_bf16 v[52:55], v[164:167], v[196:199], v[52:55]
	v_mfma_f32_16x16x32_bf16 v[48:51], v[172:175], v[196:199], v[48:51]
	v_mfma_f32_16x16x32_bf16 v[36:39], v[164:167], v[204:207], v[36:39]
	v_mfma_f32_16x16x32_bf16 v[32:35], v[172:175], v[204:207], v[32:35]
	v_mfma_f32_16x16x32_bf16 v[20:23], v[164:167], v[212:215], v[20:23]
	v_mfma_f32_16x16x32_bf16 v[16:19], v[172:175], v[212:215], v[16:19]
	v_mfma_f32_16x16x32_bf16 v[4:7], v[164:167], v[220:223], v[4:7]
	v_mfma_f32_16x16x32_bf16 v[0:3], v[172:175], v[220:223], v[0:3]
	v_mfma_f32_16x16x32_bf16 v[52:55], v[168:171], v[200:203], v[52:55]
	v_mfma_f32_16x16x32_bf16 v[48:51], v[176:179], v[200:203], v[48:51]
	v_mfma_f32_16x16x32_bf16 v[36:39], v[168:171], v[208:211], v[36:39]
	v_mfma_f32_16x16x32_bf16 v[32:35], v[176:179], v[208:211], v[32:35]
	v_mfma_f32_16x16x32_bf16 v[20:23], v[168:171], v[216:219], v[20:23]
	v_mfma_f32_16x16x32_bf16 v[16:19], v[176:179], v[216:219], v[16:19]
	s_setprio 3
	s_barrier
	v_mfma_f32_16x16x32_bf16 v[4:7], v[168:171], v[224:227], v[4:7]
	v_mfma_f32_16x16x32_bf16 v[0:3], v[176:179], v[224:227], v[0:3]
	s_setprio 0
	v_lshl_add_u64 v[228:229], v[232:233], 0, s[26:27]
	s_mov_b32 m0, s87
	s_nop 0
	s_mov_b64 exec, s[98:99]
	global_load_lds_dwordx4 v[228:229], off
	v_lshl_add_u64 v[228:229], v[234:235], 0, s[26:27]
	s_mov_b32 m0, s88
	s_nop 0
	global_load_lds_dwordx4 v[228:229], off
	s_mov_b64 exec, -1
	s_add_i32 s96, s96, 2
	s_add_u32 s70, s70, 0x100
	s_addc_u32 s71, s71, 0
	s_add_u32 s94, s94, 0x100
	s_addc_u32 s95, s95, 0
	s_cmp_gt_u32 s96, 13
	s_cbranch_scc0 .LBB0_152
	s_and_b64 vcc, exec, s[28:29]
	s_cbranch_vccz .LBB0_155
	s_barrier

.LBB0_610:
	s_add_i32 s43, s43, 1
	s_mul_i32 s4, s43, s73
	s_mul_hi_u32 s5, s43, s72
	s_add_i32 s5, s5, s4
	s_mul_i32 s4, s43, s72
	s_add_u32 s18, s4, s2
	s_addc_u32 s19, s5, s3
	v_cmp_gt_i64_e32 vcc, s[18:19], v[142:143]
	v_cmp_lt_i64_e64 s[4:5], s[18:19], v[140:141]
	s_and_b64 s[98:99], s[4:5], exec
	s_cselect_b32 s100, -1, 0
	s_cbranch_vccnz .LBB0_616
	s_ashr_i32 s14, s18, 31
	s_lshr_b32 s14, s14, 29
	s_add_i32 s16, s18, s14
	s_and_b32 s14, s16, -8
	s_sub_i32 s17, s18, s14
	s_cmp_gt_i32 s17, -1
	s_mov_b64 s[14:15], -1
	s_cbranch_scc0 .LBB0_613
	s_lshl_b32 s18, s17, 6
	s_mov_b64 s[14:15], 0

.LBB0_617:
	ds_read_b128 v[144:147], v151
	ds_read_b128 v[156:159], v151 offset:1024
	ds_read_b128 v[160:163], v151 offset:2048
	ds_read_b128 v[164:167], v151 offset:3072
	ds_read_b128 v[168:171], v152
	ds_read_b128 v[172:175], v152 offset:1024
	ds_read_b128 v[176:179], v152 offset:2048
	ds_read_b128 v[184:187], v152 offset:3072
	s_add_u32 s26, s24, 0xfffc0080
	s_addc_u32 s27, s25, -1
	s_cmp_eq_u32 s51, 12
	s_cselect_b32 s29, s17, s27
	s_cselect_b32 s28, s23, s26
	s_cselect_b32 s27, s15, s50
	s_cselect_b32 s26, s46, s47
	s_cselect_b32 s99, 0, -1
	s_or_b32 s99, s99, s100
	s_mov_b32 s98, s99
	v_lshl_add_u64 v[220:221], s[24:25], 0, v[136:137]
	s_add_i32 m0, s34, 0xc000
	ds_read_b128 v[188:191], v153
	ds_read_b128 v[192:195], v153 offset:1024
	ds_read_b128 v[196:199], v153 offset:2048
	ds_read_b128 v[200:203], v153 offset:3072
	ds_read_b128 v[204:207], v153 offset:4096
	ds_read_b128 v[208:211], v153 offset:5120
	ds_read_b128 v[212:215], v153 offset:6144
	ds_read_b128 v[216:219], v153 offset:7168
	global_load_lds_dwordx4 v[220:221], off
	v_lshl_add_u64 v[220:221], s[24:25], 0, v[138:139]
	s_add_i32 m0, s34, 0xe000
	s_nop 0
	global_load_lds_dwordx4 v[220:221], off
	s_waitcnt vmcnt(8)
	s_waitcnt lgkmcnt(0)
	s_barrier
	s_waitcnt lgkmcnt(0)
	v_mfma_f32_16x16x32_bf16 v[124:127], v[144:147], v[188:191], v[124:127]
	v_mfma_f32_16x16x32_bf16 v[120:123], v[160:163], v[188:191], v[120:123]
	v_mfma_f32_16x16x32_bf16 v[108:111], v[144:147], v[196:199], v[108:111]
	v_mfma_f32_16x16x32_bf16 v[104:107], v[160:163], v[196:199], v[104:107]
	v_mfma_f32_16x16x32_bf16 v[92:95], v[144:147], v[204:207], v[92:95]
	v_mfma_f32_16x16x32_bf16 v[88:91], v[160:163], v[204:207], v[88:91]
	v_mfma_f32_16x16x32_bf16 v[76:79], v[144:147], v[212:215], v[76:79]
	v_mfma_f32_16x16x32_bf16 v[72:75], v[160:163], v[212:215], v[72:75]
	v_mfma_f32_16x16x32_bf16 v[124:127], v[156:159], v[192:195], v[124:127]
	v_mfma_f32_16x16x32_bf16 v[120:123], v[164:167], v[192:195], v[120:123]
	v_mfma_f32_16x16x32_bf16 v[108:111], v[156:159], v[200:203], v[108:111]
	v_mfma_f32_16x16x32_bf16 v[104:107], v[164:167], v[200:203], v[104:107]
	v_mfma_f32_16x16x32_bf16 v[92:95], v[156:159], v[208:211], v[92:95]
	v_mfma_f32_16x16x32_bf16 v[88:91], v[164:167], v[208:211], v[88:91]
	v_mfma_f32_16x16x32_bf16 v[76:79], v[156:159], v[216:219], v[76:79]
	v_mfma_f32_16x16x32_bf16 v[72:75], v[164:167], v[216:219], v[72:75]
	v_mfma_f32_16x16x32_bf16 v[116:119], v[168:171], v[188:191], v[116:119]
	v_mfma_f32_16x16x32_bf16 v[112:115], v[176:179], v[188:191], v[112:115]
	v_mfma_f32_16x16x32_bf16 v[100:103], v[168:171], v[196:199], v[100:103]
	v_mfma_f32_16x16x32_bf16 v[96:99], v[176:179], v[196:199], v[96:99]
	v_mfma_f32_16x16x32_bf16 v[84:87], v[168:171], v[204:207], v[84:87]
	v_mfma_f32_16x16x32_bf16 v[80:83], v[176:179], v[204:207], v[80:83]
	v_mfma_f32_16x16x32_bf16 v[68:71], v[168:171], v[212:215], v[68:71]
	v_mfma_f32_16x16x32_bf16 v[64:67], v[176:179], v[212:215], v[64:67]
	v_mfma_f32_16x16x32_bf16 v[116:119], v[172:175], v[192:195], v[116:119]
	v_mfma_f32_16x16x32_bf16 v[112:115], v[184:187], v[192:195], v[112:115]
	v_mfma_f32_16x16x32_bf16 v[100:103], v[172:175], v[200:203], v[100:103]
	v_mfma_f32_16x16x32_bf16 v[96:99], v[184:187], v[200:203], v[96:99]
	v_mfma_f32_16x16x32_bf16 v[84:87], v[172:175], v[208:211], v[84:87]
	v_mfma_f32_16x16x32_bf16 v[80:83], v[184:187], v[208:211], v[80:83]
	s_setprio 3
	s_barrier
	v_mfma_f32_16x16x32_bf16 v[68:71], v[172:175], v[216:219], v[68:71]
	v_mfma_f32_16x16x32_bf16 v[64:67], v[184:187], v[216:219], v[64:67]
	s_setprio 0
	s_add_i32 s52, s41, s33
	v_lshl_add_u64 v[220:221], s[26:27], 0, v[130:131]
	s_mov_b32 m0, s52
	ds_read_b128 v[188:191], v153 offset:16384
	ds_read_b128 v[192:195], v153 offset:17408
	ds_read_b128 v[196:199], v153 offset:18432
	ds_read_b128 v[200:203], v153 offset:19456
	ds_read_b128 v[204:207], v153 offset:20480
	ds_read_b128 v[208:211], v153 offset:21504
	ds_read_b128 v[212:215], v153 offset:22528
	ds_read_b128 v[216:219], v153 offset:23552
	s_mov_b64 exec, s[98:99]
	global_load_lds_dwordx4 v[220:221], off
	s_add_i32 m0, s52, 0x2000
	s_add_u32 s52, s26, 0x40000
	v_lshl_add_u64 v[222:223], s[26:27], 0, v[134:135]
	s_addc_u32 s53, s27, 0
	s_add_i32 s54, s42, s33
	global_load_lds_dwordx4 v[222:223], off
	v_lshl_add_u64 v[224:225], s[52:53], 0, v[130:131]
	s_mov_b32 m0, s54
	global_load_lds_dwordx4 v[224:225], off
	v_lshl_add_u64 v[224:225], s[52:53], 0, v[134:135]
	s_add_i32 m0, s54, 0x2000
	s_nop 0
	global_load_lds_dwordx4 v[224:225], off
	s_mov_b64 exec, -1
	s_cmp_lg_u32 s99, 0
	s_cbranch_scc1 .Lng_1_1
	s_waitcnt vmcnt(0)
.Lng_1_1:
	s_waitcnt vmcnt(6)
	s_waitcnt lgkmcnt(0)
	s_barrier
	s_waitcnt lgkmcnt(0)
	v_mfma_f32_16x16x32_bf16 v[60:63], v[144:147], v[188:191], v[60:63]
	v_mfma_f32_16x16x32_bf16 v[56:59], v[160:163], v[188:191], v[56:59]
	v_mfma_f32_16x16x32_bf16 v[44:47], v[144:147], v[196:199], v[44:47]
	v_mfma_f32_16x16x32_bf16 v[40:43], v[160:163], v[196:199], v[40:43]
	v_mfma_f32_16x16x32_bf16 v[28:31], v[144:147], v[204:207], v[28:31]
	v_mfma_f32_16x16x32_bf16 v[24:27], v[160:163], v[204:207], v[24:27]
	v_mfma_f32_16x16x32_bf16 v[12:15], v[144:147], v[212:215], v[12:15]
	v_mfma_f32_16x16x32_bf16 v[8:11], v[160:163], v[212:215], v[8:11]
	v_mfma_f32_16x16x32_bf16 v[60:63], v[156:159], v[192:195], v[60:63]
	v_mfma_f32_16x16x32_bf16 v[56:59], v[164:167], v[192:195], v[56:59]
	v_mfma_f32_16x16x32_bf16 v[44:47], v[156:159], v[200:203], v[44:47]
	v_mfma_f32_16x16x32_bf16 v[40:43], v[164:167], v[200:203], v[40:43]
	v_mfma_f32_16x16x32_bf16 v[28:31], v[156:159], v[208:211], v[28:31]
	v_mfma_f32_16x16x32_bf16 v[24:27], v[164:167], v[208:211], v[24:27]
	v_mfma_f32_16x16x32_bf16 v[12:15], v[156:159], v[216:219], v[12:15]
	v_mfma_f32_16x16x32_bf16 v[8:11], v[164:167], v[216:219], v[8:11]
	v_mfma_f32_16x16x32_bf16 v[52:55], v[168:171], v[188:191], v[52:55]
	v_mfma_f32_16x16x32_bf16 v[48:51], v[176:179], v[188:191], v[48:51]
	v_mfma_f32_16x16x32_bf16 v[36:39], v[168:171], v[196:199], v[36:39]
	v_mfma_f32_16x16x32_bf16 v[32:35], v[176:179], v[196:199], v[32:35]
	v_mfma_f32_16x16x32_bf16 v[20:23], v[168:171], v[204:207], v[20:23]
	v_mfma_f32_16x16x32_bf16 v[16:19], v[176:179], v[204:207], v[16:19]
	v_mfma_f32_16x16x32_bf16 v[4:7], v[168:171], v[212:215], v[4:7]
	v_mfma_f32_16x16x32_bf16 v[0:3], v[176:179], v[212:215], v[0:3]
	v_mfma_f32_16x16x32_bf16 v[52:55], v[172:175], v[192:195], v[52:55]
	v_mfma_f32_16x16x32_bf16 v[48:51], v[184:187], v[192:195], v[48:51]
	v_mfma_f32_16x16x32_bf16 v[36:39], v[172:175], v[200:203], v[36:39]
	v_mfma_f32_16x16x32_bf16 v[32:35], v[184:187], v[200:203], v[32:35]
	v_mfma_f32_16x16x32_bf16 v[20:23], v[172:175], v[208:211], v[20:23]
	v_mfma_f32_16x16x32_bf16 v[16:19], v[184:187], v[208:211], v[16:19]
	s_setprio 3
	s_barrier
	v_mfma_f32_16x16x32_bf16 v[4:7], v[172:175], v[216:219], v[4:7]
	v_mfma_f32_16x16x32_bf16 v[0:3], v[184:187], v[216:219], v[0:3]
	s_setprio 0
	s_add_i32 s52, 0, 0x18000
	v_add_u32_e32 v155, s52, v149
	s_add_i32 s53, 0, 0x1c000
	ds_read_b128 v[144:147], v155
	ds_read_b128 v[156:159], v155 offset:1024
	ds_read_b128 v[160:163], v155 offset:2048
	ds_read_b128 v[164:167], v155 offset:3072
	v_add_u32_e32 v155, s53, v149
	ds_read_b128 v[168:171], v155
	ds_read_b128 v[172:175], v155 offset:1024
	ds_read_b128 v[176:179], v155 offset:2048
	ds_read_b128 v[184:187], v155 offset:3072
	v_lshl_add_u64 v[224:225], s[28:29], 0, v[128:129]
	s_mov_b32 m0, s34
	v_lshl_add_u64 v[226:227], s[28:29], 0, v[132:133]
	s_mov_b64 exec, s[98:99]
	global_load_lds_dwordx4 v[224:225], off
	s_mov_b32 m0, s35
	s_nop 0
	global_load_lds_dwordx4 v[226:227], off
	s_mov_b64 exec, -1
	s_add_u32 s28, s28, 0x40000
	s_addc_u32 s29, s29, 0
	s_mov_b32 m0, s36
	v_lshl_add_u64 v[228:229], s[28:29], 0, v[128:129]
	ds_read_b128 v[188:191], v153 offset:32768
	ds_read_b128 v[192:195], v153 offset:33792
	ds_read_b128 v[196:199], v153 offset:34816
	ds_read_b128 v[200:203], v153 offset:35840
	ds_read_b128 v[204:207], v153 offset:36864
	ds_read_b128 v[208:211], v153 offset:37888
	ds_read_b128 v[212:215], v153 offset:38912
	ds_read_b128 v[216:219], v153 offset:39936
	s_mov_b64 exec, s[98:99]
	global_load_lds_dwordx4 v[228:229], off
	v_lshl_add_u64 v[228:229], s[28:29], 0, v[132:133]
	s_mov_b32 m0, s37
	s_nop 0
	global_load_lds_dwordx4 v[228:229], off
	s_mov_b64 exec, -1
	s_cmp_lg_u32 s99, 0
	s_cbranch_scc1 .Lng_1_2
	s_waitcnt vmcnt(0)
.Lng_1_2:
	s_waitcnt vmcnt(8)
	s_waitcnt lgkmcnt(0)
	s_barrier
	s_waitcnt lgkmcnt(0)
	v_mfma_f32_16x16x32_bf16 v[124:127], v[144:147], v[188:191], v[124:127]
	v_mfma_f32_16x16x32_bf16 v[120:123], v[160:163], v[188:191], v[120:123]
	v_mfma_f32_16x16x32_bf16 v[108:111], v[144:147], v[196:199], v[108:111]
	v_mfma_f32_16x16x32_bf16 v[104:107], v[160:163], v[196:199], v[104:107]
	v_mfma_f32_16x16x32_bf16 v[92:95], v[144:147], v[204:207], v[92:95]
	v_mfma_f32_16x16x32_bf16 v[88:91], v[160:163], v[204:207], v[88:91]
	v_mfma_f32_16x16x32_bf16 v[76:79], v[144:147], v[212:215], v[76:79]
	v_mfma_f32_16x16x32_bf16 v[72:75], v[160:163], v[212:215], v[72:75]
	v_mfma_f32_16x16x32_bf16 v[124:127], v[156:159], v[192:195], v[124:127]
	v_mfma_f32_16x16x32_bf16 v[120:123], v[164:167], v[192:195], v[120:123]
	v_mfma_f32_16x16x32_bf16 v[108:111], v[156:159], v[200:203], v[108:111]
	v_mfma_f32_16x16x32_bf16 v[104:107], v[164:167], v[200:203], v[104:107]
	v_mfma_f32_16x16x32_bf16 v[92:95], v[156:159], v[208:211], v[92:95]
	v_mfma_f32_16x16x32_bf16 v[88:91], v[164:167], v[208:211], v[88:91]
	v_mfma_f32_16x16x32_bf16 v[76:79], v[156:159], v[216:219], v[76:79]
	v_mfma_f32_16x16x32_bf16 v[72:75], v[164:167], v[216:219], v[72:75]
	v_mfma_f32_16x16x32_bf16 v[116:119], v[168:171], v[188:191], v[116:119]
	v_mfma_f32_16x16x32_bf16 v[112:115], v[176:179], v[188:191], v[112:115]
	v_mfma_f32_16x16x32_bf16 v[100:103], v[168:171], v[196:199], v[100:103]
	v_mfma_f32_16x16x32_bf16 v[96:99], v[176:179], v[196:199], v[96:99]
	v_mfma_f32_16x16x32_bf16 v[84:87], v[168:171], v[204:207], v[84:87]
	v_mfma_f32_16x16x32_bf16 v[80:83], v[176:179], v[204:207], v[80:83]
	v_mfma_f32_16x16x32_bf16 v[68:71], v[168:171], v[212:215], v[68:71]
	v_mfma_f32_16x16x32_bf16 v[64:67], v[176:179], v[212:215], v[64:67]
	v_mfma_f32_16x16x32_bf16 v[116:119], v[172:175], v[192:195], v[116:119]
	v_mfma_f32_16x16x32_bf16 v[112:115], v[184:187], v[192:195], v[112:115]
	v_mfma_f32_16x16x32_bf16 v[100:103], v[172:175], v[200:203], v[100:103]
	v_mfma_f32_16x16x32_bf16 v[96:99], v[184:187], v[200:203], v[96:99]
	v_mfma_f32_16x16x32_bf16 v[84:87], v[172:175], v[208:211], v[84:87]
	v_mfma_f32_16x16x32_bf16 v[80:83], v[184:187], v[208:211], v[80:83]
	s_setprio 3
	s_barrier
	v_mfma_f32_16x16x32_bf16 v[68:71], v[172:175], v[216:219], v[68:71]
	v_mfma_f32_16x16x32_bf16 v[64:67], v[184:187], v[216:219], v[64:67]
	s_setprio 0
	s_add_i32 s28, s52, s33
	v_lshl_add_u64 v[220:221], v[220:221], 0, s[10:11]
	s_mov_b32 m0, s28
	ds_read_b128 v[188:191], v153 offset:49152
	ds_read_b128 v[192:195], v153 offset:50176
	ds_read_b128 v[196:199], v153 offset:51200
	ds_read_b128 v[200:203], v153 offset:52224
	ds_read_b128 v[204:207], v153 offset:53248
	ds_read_b128 v[208:211], v153 offset:54272
	ds_read_b128 v[212:215], v153 offset:55296
	ds_read_b128 v[216:219], v153 offset:56320
	s_mov_b64 exec, s[98:99]
	global_load_lds_dwordx4 v[220:221], off
	s_add_i32 m0, s28, 0x2000
	s_add_u32 s26, s26, 0x40080
	v_lshl_add_u64 v[220:221], v[222:223], 0, s[10:11]
	s_addc_u32 s27, s27, 0
	s_add_i32 s28, s53, s33
	global_load_lds_dwordx4 v[220:221], off
	v_lshl_add_u64 v[220:221], s[26:27], 0, v[130:131]
	s_mov_b32 m0, s28
	s_nop 0
	global_load_lds_dwordx4 v[220:221], off
	v_lshl_add_u64 v[220:221], s[26:27], 0, v[134:135]
	s_add_i32 m0, s28, 0x2000
	s_nop 0
	global_load_lds_dwordx4 v[220:221], off
	s_mov_b64 exec, -1
	s_cmp_lg_u32 s99, 0
	s_cbranch_scc1 .Lng_1_3
	s_waitcnt vmcnt(0)
.Lng_1_3:
	s_waitcnt vmcnt(6)
	s_waitcnt lgkmcnt(0)
	s_barrier
	s_waitcnt lgkmcnt(0)
	v_mfma_f32_16x16x32_bf16 v[60:63], v[144:147], v[188:191], v[60:63]
	v_mfma_f32_16x16x32_bf16 v[56:59], v[160:163], v[188:191], v[56:59]
	v_mfma_f32_16x16x32_bf16 v[44:47], v[144:147], v[196:199], v[44:47]
	v_mfma_f32_16x16x32_bf16 v[40:43], v[160:163], v[196:199], v[40:43]
	v_mfma_f32_16x16x32_bf16 v[28:31], v[144:147], v[204:207], v[28:31]
	v_mfma_f32_16x16x32_bf16 v[24:27], v[160:163], v[204:207], v[24:27]
	v_mfma_f32_16x16x32_bf16 v[12:15], v[144:147], v[212:215], v[12:15]
	v_mfma_f32_16x16x32_bf16 v[8:11], v[160:163], v[212:215], v[8:11]
	v_mfma_f32_16x16x32_bf16 v[60:63], v[156:159], v[192:195], v[60:63]
	v_mfma_f32_16x16x32_bf16 v[56:59], v[164:167], v[192:195], v[56:59]
	v_mfma_f32_16x16x32_bf16 v[44:47], v[156:159], v[200:203], v[44:47]
	v_mfma_f32_16x16x32_bf16 v[40:43], v[164:167], v[200:203], v[40:43]
	v_mfma_f32_16x16x32_bf16 v[28:31], v[156:159], v[208:211], v[28:31]
	v_mfma_f32_16x16x32_bf16 v[24:27], v[164:167], v[208:211], v[24:27]
	v_mfma_f32_16x16x32_bf16 v[12:15], v[156:159], v[216:219], v[12:15]
	v_mfma_f32_16x16x32_bf16 v[8:11], v[164:167], v[216:219], v[8:11]
	v_mfma_f32_16x16x32_bf16 v[52:55], v[168:171], v[188:191], v[52:55]
	v_mfma_f32_16x16x32_bf16 v[48:51], v[176:179], v[188:191], v[48:51]
	v_mfma_f32_16x16x32_bf16 v[36:39], v[168:171], v[196:199], v[36:39]
	v_mfma_f32_16x16x32_bf16 v[32:35], v[176:179], v[196:199], v[32:35]
	v_mfma_f32_16x16x32_bf16 v[20:23], v[168:171], v[204:207], v[20:23]
	v_mfma_f32_16x16x32_bf16 v[16:19], v[176:179], v[204:207], v[16:19]
	v_mfma_f32_16x16x32_bf16 v[4:7], v[168:171], v[212:215], v[4:7]
	v_mfma_f32_16x16x32_bf16 v[0:3], v[176:179], v[212:215], v[0:3]
	v_mfma_f32_16x16x32_bf16 v[52:55], v[172:175], v[192:195], v[52:55]
	v_mfma_f32_16x16x32_bf16 v[48:51], v[184:187], v[192:195], v[48:51]
	v_mfma_f32_16x16x32_bf16 v[36:39], v[172:175], v[200:203], v[36:39]
	v_mfma_f32_16x16x32_bf16 v[32:35], v[184:187], v[200:203], v[32:35]
	v_mfma_f32_16x16x32_bf16 v[20:23], v[172:175], v[208:211], v[20:23]
	v_mfma_f32_16x16x32_bf16 v[16:19], v[184:187], v[208:211], v[16:19]
	s_setprio 3
	s_barrier
	v_mfma_f32_16x16x32_bf16 v[4:7], v[172:175], v[216:219], v[4:7]
	v_mfma_f32_16x16x32_bf16 v[0:3], v[184:187], v[216:219], v[0:3]
	s_setprio 0
	v_lshl_add_u64 v[220:221], v[224:225], 0, s[10:11]
	s_mov_b32 m0, s39
	s_nop 0
	s_mov_b64 exec, s[98:99]
	global_load_lds_dwordx4 v[220:221], off
	v_lshl_add_u64 v[220:221], v[226:227], 0, s[10:11]
	s_mov_b32 m0, s40
	s_nop 0
	global_load_lds_dwordx4 v[220:221], off
	s_mov_b64 exec, -1
	s_add_i32 s51, s51, 2
	s_add_u32 s24, s24, 0x100
	s_addc_u32 s25, s25, 0
	s_add_u32 s47, s47, 0x100
	s_addc_u32 s50, s50, 0
	s_cmp_gt_u32 s51, 13
	s_cbranch_scc0 .LBB0_617
	s_and_b64 vcc, exec, s[12:13]
	s_cbranch_vccz .LBB0_620
	s_barrier

.LBB0_702:
	s_add_i32 s39, s40, 1
	s_mul_i32 s0, s39, s73
	s_mul_hi_u32 s1, s39, s72
	s_add_i32 s1, s1, s0
	s_mul_i32 s0, s39, s72
	s_add_u32 s14, s0, s2
	s_addc_u32 s15, s1, s3
	v_cmp_gt_i64_e32 vcc, s[14:15], v[142:143]
	v_cmp_lt_i64_e64 s[0:1], s[14:15], v[140:141]
	s_and_b64 s[98:99], s[0:1], exec
	s_cselect_b32 s100, -1, 0
	s_cbranch_vccnz .LBB0_704
	s_ashr_i32 s10, s14, 31
	s_lshr_b32 s10, s10, 29
	s_add_i32 s10, s14, s10
	s_ashr_i32 s11, s10, 3
	s_and_b32 s10, s10, -8
	s_sub_i32 s10, s14, s10
	s_cmp_lt_i32 s10, 0
	s_cselect_b32 s12, s29, 0x160
	s_mul_i32 s10, s12, s10
	s_add_i32 s10, s10, s11
	s_mul_hi_i32 s11, s10, 0x2e8ba2e9
	s_lshr_b32 s12, s11, 31
	s_ashr_i32 s11, s11, 5
	s_add_i32 s11, s11, s12
	s_lshl_b32 s12, s11, 3
	s_sub_i32 s13, 0x80, s12
	s_min_i32 s13, s13, 8
	s_abs_i32 s14, s13
	v_cvt_f32_u32_e32 v0, s14
	s_sub_i32 s16, 0, s14
	s_mulk_i32 s11, 0xb0
	s_sub_i32 s11, s10, s11
	v_rcp_iflag_f32_e32 v0, v0
	s_abs_i32 s10, s11
	s_xor_b32 s15, s11, s13
	s_ashr_i32 s15, s15, 31
	v_mul_f32_e32 v0, 0x4f7ffffe, v0
	v_cvt_u32_f32_e32 v0, v0
	s_nop 0
	v_readfirstlane_b32 s17, v0
	s_mul_i32 s16, s16, s17
	s_mul_hi_u32 s16, s17, s16
	s_add_i32 s17, s17, s16
	s_mul_hi_u32 s16, s10, s17
	s_mul_i32 s17, s16, s14
	s_sub_i32 s10, s10, s17
	s_add_i32 s24, s16, 1
	s_sub_i32 s17, s10, s14
	s_cmp_ge_u32 s10, s14
	s_cselect_b32 s16, s24, s16
	s_cselect_b32 s10, s17, s10
	s_add_i32 s17, s16, 1
	s_cmp_ge_u32 s10, s14
	s_cselect_b32 s10, s17, s16
	s_xor_b32 s10, s10, s15
	s_sub_i32 s10, s10, s15
	s_mul_i32 s13, s10, s13
	s_sub_i32 s11, s11, s13
	s_add_i32 s12, s11, s12

.LBB0_705:
	ds_read_b128 v[154:157], v151
	ds_read_b128 v[158:161], v151 offset:1024
	ds_read_b128 v[162:165], v151 offset:2048
	ds_read_b128 v[166:169], v151 offset:3072
	ds_read_b128 v[170:173], v152
	ds_read_b128 v[174:177], v152 offset:1024
	ds_read_b128 v[184:187], v152 offset:2048
	ds_read_b128 v[188:191], v152 offset:3072
	s_add_u32 s22, s20, 0xfffc0080
	s_addc_u32 s23, s21, -1
	s_cmp_eq_u32 s50, 12
	s_cselect_b32 s25, s13, s23
	s_cselect_b32 s24, s42, s22
	s_cselect_b32 s23, s11, s47
	s_cselect_b32 s22, s43, s46
	s_cselect_b32 s99, 0, -1
	s_or_b32 s99, s99, s100
	s_mov_b32 s98, s99
	v_lshl_add_u64 v[178:179], s[20:21], 0, v[136:137]
	s_add_i32 m0, s19, 0xc000
	ds_read_b128 v[192:195], v153
	ds_read_b128 v[196:199], v153 offset:1024
	ds_read_b128 v[200:203], v153 offset:2048
	ds_read_b128 v[204:207], v153 offset:3072
	ds_read_b128 v[208:211], v153 offset:4096
	ds_read_b128 v[212:215], v153 offset:5120
	ds_read_b128 v[216:219], v153 offset:6144
	ds_read_b128 v[220:223], v153 offset:7168
	global_load_lds_dwordx4 v[178:179], off
	v_lshl_add_u64 v[178:179], s[20:21], 0, v[138:139]
	s_add_i32 m0, s19, 0xe000
	s_nop 0
	global_load_lds_dwordx4 v[178:179], off
	s_waitcnt vmcnt(8)
	s_waitcnt lgkmcnt(0)
	s_barrier
	s_waitcnt lgkmcnt(0)
	v_mfma_f32_16x16x32_bf16 v[124:127], v[154:157], v[192:195], v[124:127]
	v_mfma_f32_16x16x32_bf16 v[116:119], v[162:165], v[192:195], v[116:119]
	v_mfma_f32_16x16x32_bf16 v[108:111], v[154:157], v[200:203], v[108:111]
	v_mfma_f32_16x16x32_bf16 v[100:103], v[162:165], v[200:203], v[100:103]
	v_mfma_f32_16x16x32_bf16 v[92:95], v[154:157], v[208:211], v[92:95]
	v_mfma_f32_16x16x32_bf16 v[84:87], v[162:165], v[208:211], v[84:87]
	v_mfma_f32_16x16x32_bf16 v[76:79], v[154:157], v[216:219], v[76:79]
	v_mfma_f32_16x16x32_bf16 v[68:71], v[162:165], v[216:219], v[68:71]
	v_mfma_f32_16x16x32_bf16 v[124:127], v[158:161], v[196:199], v[124:127]
	v_mfma_f32_16x16x32_bf16 v[116:119], v[166:169], v[196:199], v[116:119]
	v_mfma_f32_16x16x32_bf16 v[108:111], v[158:161], v[204:207], v[108:111]
	v_mfma_f32_16x16x32_bf16 v[100:103], v[166:169], v[204:207], v[100:103]
	v_mfma_f32_16x16x32_bf16 v[92:95], v[158:161], v[212:215], v[92:95]
	v_mfma_f32_16x16x32_bf16 v[84:87], v[166:169], v[212:215], v[84:87]
	v_mfma_f32_16x16x32_bf16 v[76:79], v[158:161], v[220:223], v[76:79]
	v_mfma_f32_16x16x32_bf16 v[68:71], v[166:169], v[220:223], v[68:71]
	v_mfma_f32_16x16x32_bf16 v[120:123], v[170:173], v[192:195], v[120:123]
	v_mfma_f32_16x16x32_bf16 v[112:115], v[184:187], v[192:195], v[112:115]
	v_mfma_f32_16x16x32_bf16 v[104:107], v[170:173], v[200:203], v[104:107]
	v_mfma_f32_16x16x32_bf16 v[96:99], v[184:187], v[200:203], v[96:99]
	v_mfma_f32_16x16x32_bf16 v[88:91], v[170:173], v[208:211], v[88:91]
	v_mfma_f32_16x16x32_bf16 v[80:83], v[184:187], v[208:211], v[80:83]
	v_mfma_f32_16x16x32_bf16 v[72:75], v[170:173], v[216:219], v[72:75]
	v_mfma_f32_16x16x32_bf16 v[64:67], v[184:187], v[216:219], v[64:67]
	v_mfma_f32_16x16x32_bf16 v[120:123], v[174:177], v[196:199], v[120:123]
	v_mfma_f32_16x16x32_bf16 v[112:115], v[188:191], v[196:199], v[112:115]
	v_mfma_f32_16x16x32_bf16 v[104:107], v[174:177], v[204:207], v[104:107]
	v_mfma_f32_16x16x32_bf16 v[96:99], v[188:191], v[204:207], v[96:99]
	v_mfma_f32_16x16x32_bf16 v[88:91], v[174:177], v[212:215], v[88:91]
	v_mfma_f32_16x16x32_bf16 v[80:83], v[188:191], v[212:215], v[80:83]
	s_setprio 3
	s_barrier
	v_mfma_f32_16x16x32_bf16 v[72:75], v[174:177], v[220:223], v[72:75]
	v_mfma_f32_16x16x32_bf16 v[64:67], v[188:191], v[220:223], v[64:67]
	s_setprio 0
	s_add_i32 s51, s36, s28
	v_lshl_add_u64 v[178:179], s[22:23], 0, v[132:133]
	s_mov_b32 m0, s51
	ds_read_b128 v[192:195], v153 offset:16384
	ds_read_b128 v[196:199], v153 offset:17408
	ds_read_b128 v[200:203], v153 offset:18432
	ds_read_b128 v[204:207], v153 offset:19456
	ds_read_b128 v[208:211], v153 offset:20480
	ds_read_b128 v[212:215], v153 offset:21504
	ds_read_b128 v[216:219], v153 offset:22528
	ds_read_b128 v[220:223], v153 offset:23552
	s_mov_b64 exec, s[98:99]
	global_load_lds_dwordx4 v[178:179], off
	s_add_i32 m0, s51, 0x2000
	s_add_u32 s52, s22, 0x40000
	v_lshl_add_u64 v[224:225], s[22:23], 0, v[128:129]
	s_addc_u32 s53, s23, 0
	s_add_i32 s51, s37, s28
	global_load_lds_dwordx4 v[224:225], off
	v_lshl_add_u64 v[226:227], s[52:53], 0, v[132:133]
	s_mov_b32 m0, s51
	global_load_lds_dwordx4 v[226:227], off
	v_lshl_add_u64 v[226:227], s[52:53], 0, v[128:129]
	s_add_i32 m0, s51, 0x2000
	s_nop 0
	global_load_lds_dwordx4 v[226:227], off
	s_mov_b64 exec, -1
	s_cmp_lg_u32 s99, 0
	s_cbranch_scc1 .Lng_2_1
	s_waitcnt vmcnt(0)
.Lng_2_1:
	s_waitcnt vmcnt(6)
	s_waitcnt lgkmcnt(0)
	s_barrier
	s_waitcnt lgkmcnt(0)
	v_mfma_f32_16x16x32_bf16 v[60:63], v[154:157], v[192:195], v[60:63]
	v_mfma_f32_16x16x32_bf16 v[52:55], v[162:165], v[192:195], v[52:55]
	v_mfma_f32_16x16x32_bf16 v[44:47], v[154:157], v[200:203], v[44:47]
	v_mfma_f32_16x16x32_bf16 v[36:39], v[162:165], v[200:203], v[36:39]
	v_mfma_f32_16x16x32_bf16 v[28:31], v[154:157], v[208:211], v[28:31]
	v_mfma_f32_16x16x32_bf16 v[20:23], v[162:165], v[208:211], v[20:23]
	v_mfma_f32_16x16x32_bf16 v[12:15], v[154:157], v[216:219], v[12:15]
	v_mfma_f32_16x16x32_bf16 v[4:7], v[162:165], v[216:219], v[4:7]
	v_mfma_f32_16x16x32_bf16 v[60:63], v[158:161], v[196:199], v[60:63]
	v_mfma_f32_16x16x32_bf16 v[52:55], v[166:169], v[196:199], v[52:55]
	v_mfma_f32_16x16x32_bf16 v[44:47], v[158:161], v[204:207], v[44:47]
	v_mfma_f32_16x16x32_bf16 v[36:39], v[166:169], v[204:207], v[36:39]
	v_mfma_f32_16x16x32_bf16 v[28:31], v[158:161], v[212:215], v[28:31]
	v_mfma_f32_16x16x32_bf16 v[20:23], v[166:169], v[212:215], v[20:23]
	v_mfma_f32_16x16x32_bf16 v[12:15], v[158:161], v[220:223], v[12:15]
	v_mfma_f32_16x16x32_bf16 v[4:7], v[166:169], v[220:223], v[4:7]
	v_mfma_f32_16x16x32_bf16 v[56:59], v[170:173], v[192:195], v[56:59]
	v_mfma_f32_16x16x32_bf16 v[48:51], v[184:187], v[192:195], v[48:51]
	v_mfma_f32_16x16x32_bf16 v[40:43], v[170:173], v[200:203], v[40:43]
	v_mfma_f32_16x16x32_bf16 v[32:35], v[184:187], v[200:203], v[32:35]
	v_mfma_f32_16x16x32_bf16 v[24:27], v[170:173], v[208:211], v[24:27]
	v_mfma_f32_16x16x32_bf16 v[16:19], v[184:187], v[208:211], v[16:19]
	v_mfma_f32_16x16x32_bf16 v[8:11], v[170:173], v[216:219], v[8:11]
	v_mfma_f32_16x16x32_bf16 v[0:3], v[184:187], v[216:219], v[0:3]
	v_mfma_f32_16x16x32_bf16 v[56:59], v[174:177], v[196:199], v[56:59]
	v_mfma_f32_16x16x32_bf16 v[48:51], v[188:191], v[196:199], v[48:51]
	v_mfma_f32_16x16x32_bf16 v[40:43], v[174:177], v[204:207], v[40:43]
	v_mfma_f32_16x16x32_bf16 v[32:35], v[188:191], v[204:207], v[32:35]
	v_mfma_f32_16x16x32_bf16 v[24:27], v[174:177], v[212:215], v[24:27]
	v_mfma_f32_16x16x32_bf16 v[16:19], v[188:191], v[212:215], v[16:19]
	s_setprio 3
	s_barrier
	v_mfma_f32_16x16x32_bf16 v[8:11], v[174:177], v[220:223], v[8:11]
	v_mfma_f32_16x16x32_bf16 v[0:3], v[188:191], v[220:223], v[0:3]
	s_setprio 0
	s_add_i32 s51, 0, 0x18000
	s_add_i32 s52, 0, 0x1c000
	v_add_u32_e32 v166, s51, v145
	v_add_u32_e32 v180, s52, v145
	ds_read_b128 v[154:157], v166
	ds_read_b128 v[158:161], v166 offset:1024
	ds_read_b128 v[162:165], v166 offset:2048
	ds_read_b128 v[166:169], v166 offset:3072
	ds_read_b128 v[170:173], v180
	ds_read_b128 v[174:177], v180 offset:1024
	ds_read_b128 v[184:187], v180 offset:2048
	ds_read_b128 v[188:191], v180 offset:3072
	v_lshl_add_u64 v[226:227], s[24:25], 0, v[134:135]
	s_mov_b32 m0, s19
	v_lshl_add_u64 v[228:229], s[24:25], 0, v[130:131]
	s_mov_b64 exec, s[98:99]
	global_load_lds_dwordx4 v[226:227], off
	s_mov_b32 m0, s30
	s_nop 0
	global_load_lds_dwordx4 v[228:229], off
	s_mov_b64 exec, -1
	s_add_u32 s24, s24, 0x40000
	s_addc_u32 s25, s25, 0
	s_mov_b32 m0, s31
	v_lshl_add_u64 v[230:231], s[24:25], 0, v[134:135]
	ds_read_b128 v[192:195], v153 offset:32768
	ds_read_b128 v[196:199], v153 offset:33792
	ds_read_b128 v[200:203], v153 offset:34816
	ds_read_b128 v[204:207], v153 offset:35840
	ds_read_b128 v[208:211], v153 offset:36864
	ds_read_b128 v[212:215], v153 offset:37888
	ds_read_b128 v[216:219], v153 offset:38912
	ds_read_b128 v[220:223], v153 offset:39936
	s_mov_b64 exec, s[98:99]
	global_load_lds_dwordx4 v[230:231], off
	v_lshl_add_u64 v[230:231], s[24:25], 0, v[130:131]
	s_mov_b32 m0, s33
	s_nop 0
	global_load_lds_dwordx4 v[230:231], off
	s_mov_b64 exec, -1
	s_cmp_lg_u32 s99, 0
	s_cbranch_scc1 .Lng_2_2
	s_waitcnt vmcnt(0)
.Lng_2_2:
	s_waitcnt vmcnt(8)
	s_waitcnt lgkmcnt(0)
	s_barrier
	s_waitcnt lgkmcnt(0)
	v_mfma_f32_16x16x32_bf16 v[124:127], v[154:157], v[192:195], v[124:127]
	v_mfma_f32_16x16x32_bf16 v[116:119], v[162:165], v[192:195], v[116:119]
	v_mfma_f32_16x16x32_bf16 v[108:111], v[154:157], v[200:203], v[108:111]
	v_mfma_f32_16x16x32_bf16 v[100:103], v[162:165], v[200:203], v[100:103]
	v_mfma_f32_16x16x32_bf16 v[92:95], v[154:157], v[208:211], v[92:95]
	v_mfma_f32_16x16x32_bf16 v[84:87], v[162:165], v[208:211], v[84:87]
	v_mfma_f32_16x16x32_bf16 v[76:79], v[154:157], v[216:219], v[76:79]
	v_mfma_f32_16x16x32_bf16 v[68:71], v[162:165], v[216:219], v[68:71]
	v_mfma_f32_16x16x32_bf16 v[124:127], v[158:161], v[196:199], v[124:127]
	v_mfma_f32_16x16x32_bf16 v[116:119], v[166:169], v[196:199], v[116:119]
	v_mfma_f32_16x16x32_bf16 v[108:111], v[158:161], v[204:207], v[108:111]
	v_mfma_f32_16x16x32_bf16 v[100:103], v[166:169], v[204:207], v[100:103]
	v_mfma_f32_16x16x32_bf16 v[92:95], v[158:161], v[212:215], v[92:95]
	v_mfma_f32_16x16x32_bf16 v[84:87], v[166:169], v[212:215], v[84:87]
	v_mfma_f32_16x16x32_bf16 v[76:79], v[158:161], v[220:223], v[76:79]
	v_mfma_f32_16x16x32_bf16 v[68:71], v[166:169], v[220:223], v[68:71]
	v_mfma_f32_16x16x32_bf16 v[120:123], v[170:173], v[192:195], v[120:123]
	v_mfma_f32_16x16x32_bf16 v[112:115], v[184:187], v[192:195], v[112:115]
	v_mfma_f32_16x16x32_bf16 v[104:107], v[170:173], v[200:203], v[104:107]
	v_mfma_f32_16x16x32_bf16 v[96:99], v[184:187], v[200:203], v[96:99]
	v_mfma_f32_16x16x32_bf16 v[88:91], v[170:173], v[208:211], v[88:91]
	v_mfma_f32_16x16x32_bf16 v[80:83], v[184:187], v[208:211], v[80:83]
	v_mfma_f32_16x16x32_bf16 v[72:75], v[170:173], v[216:219], v[72:75]
	v_mfma_f32_16x16x32_bf16 v[64:67], v[184:187], v[216:219], v[64:67]
	v_mfma_f32_16x16x32_bf16 v[120:123], v[174:177], v[196:199], v[120:123]
	v_mfma_f32_16x16x32_bf16 v[112:115], v[188:191], v[196:199], v[112:115]
	v_mfma_f32_16x16x32_bf16 v[104:107], v[174:177], v[204:207], v[104:107]
	v_mfma_f32_16x16x32_bf16 v[96:99], v[188:191], v[204:207], v[96:99]
	v_mfma_f32_16x16x32_bf16 v[88:91], v[174:177], v[212:215], v[88:91]
	v_mfma_f32_16x16x32_bf16 v[80:83], v[188:191], v[212:215], v[80:83]
	s_setprio 3
	s_barrier
	v_mfma_f32_16x16x32_bf16 v[72:75], v[174:177], v[220:223], v[72:75]
	v_mfma_f32_16x16x32_bf16 v[64:67], v[188:191], v[220:223], v[64:67]
	s_setprio 0
	s_add_i32 s24, s51, s28
	v_lshl_add_u64 v[178:179], v[178:179], 0, s[6:7]
	s_mov_b32 m0, s24
	ds_read_b128 v[192:195], v153 offset:49152
	ds_read_b128 v[196:199], v153 offset:50176
	ds_read_b128 v[200:203], v153 offset:51200
	ds_read_b128 v[204:207], v153 offset:52224
	ds_read_b128 v[208:211], v153 offset:53248
	ds_read_b128 v[212:215], v153 offset:54272
	ds_read_b128 v[216:219], v153 offset:55296
	ds_read_b128 v[220:223], v153 offset:56320
	s_mov_b64 exec, s[98:99]
	global_load_lds_dwordx4 v[178:179], off
	s_add_i32 m0, s24, 0x2000
	s_add_u32 s22, s22, 0x40080
	v_lshl_add_u64 v[178:179], v[224:225], 0, s[6:7]
	s_addc_u32 s23, s23, 0
	s_add_i32 s24, s52, s28
	global_load_lds_dwordx4 v[178:179], off
	v_lshl_add_u64 v[178:179], s[22:23], 0, v[132:133]
	s_mov_b32 m0, s24
	s_nop 0
	global_load_lds_dwordx4 v[178:179], off
	v_lshl_add_u64 v[178:179], s[22:23], 0, v[128:129]
	s_add_i32 m0, s24, 0x2000
	s_nop 0
	global_load_lds_dwordx4 v[178:179], off
	s_mov_b64 exec, -1
	s_cmp_lg_u32 s99, 0
	s_cbranch_scc1 .Lng_2_3
	s_waitcnt vmcnt(0)
.Lng_2_3:
	s_waitcnt vmcnt(6)
	s_waitcnt lgkmcnt(0)
	s_barrier
	s_waitcnt lgkmcnt(0)
	v_mfma_f32_16x16x32_bf16 v[60:63], v[154:157], v[192:195], v[60:63]
	v_mfma_f32_16x16x32_bf16 v[52:55], v[162:165], v[192:195], v[52:55]
	v_mfma_f32_16x16x32_bf16 v[44:47], v[154:157], v[200:203], v[44:47]
	v_mfma_f32_16x16x32_bf16 v[36:39], v[162:165], v[200:203], v[36:39]
	v_mfma_f32_16x16x32_bf16 v[28:31], v[154:157], v[208:211], v[28:31]
	v_mfma_f32_16x16x32_bf16 v[20:23], v[162:165], v[208:211], v[20:23]
	v_mfma_f32_16x16x32_bf16 v[12:15], v[154:157], v[216:219], v[12:15]
	v_mfma_f32_16x16x32_bf16 v[4:7], v[162:165], v[216:219], v[4:7]
	v_mfma_f32_16x16x32_bf16 v[60:63], v[158:161], v[196:199], v[60:63]
	v_mfma_f32_16x16x32_bf16 v[52:55], v[166:169], v[196:199], v[52:55]
	v_mfma_f32_16x16x32_bf16 v[44:47], v[158:161], v[204:207], v[44:47]
	v_mfma_f32_16x16x32_bf16 v[36:39], v[166:169], v[204:207], v[36:39]
	v_mfma_f32_16x16x32_bf16 v[28:31], v[158:161], v[212:215], v[28:31]
	v_mfma_f32_16x16x32_bf16 v[20:23], v[166:169], v[212:215], v[20:23]
	v_mfma_f32_16x16x32_bf16 v[12:15], v[158:161], v[220:223], v[12:15]
	v_mfma_f32_16x16x32_bf16 v[4:7], v[166:169], v[220:223], v[4:7]
	v_mfma_f32_16x16x32_bf16 v[56:59], v[170:173], v[192:195], v[56:59]
	v_mfma_f32_16x16x32_bf16 v[48:51], v[184:187], v[192:195], v[48:51]
	v_mfma_f32_16x16x32_bf16 v[40:43], v[170:173], v[200:203], v[40:43]
	v_mfma_f32_16x16x32_bf16 v[32:35], v[184:187], v[200:203], v[32:35]
	v_mfma_f32_16x16x32_bf16 v[24:27], v[170:173], v[208:211], v[24:27]
	v_mfma_f32_16x16x32_bf16 v[16:19], v[184:187], v[208:211], v[16:19]
	v_mfma_f32_16x16x32_bf16 v[8:11], v[170:173], v[216:219], v[8:11]
	v_mfma_f32_16x16x32_bf16 v[0:3], v[184:187], v[216:219], v[0:3]
	v_mfma_f32_16x16x32_bf16 v[56:59], v[174:177], v[196:199], v[56:59]
	v_mfma_f32_16x16x32_bf16 v[48:51], v[188:191], v[196:199], v[48:51]
	v_mfma_f32_16x16x32_bf16 v[40:43], v[174:177], v[204:207], v[40:43]
	v_mfma_f32_16x16x32_bf16 v[32:35], v[188:191], v[204:207], v[32:35]
	v_mfma_f32_16x16x32_bf16 v[24:27], v[174:177], v[212:215], v[24:27]
	v_mfma_f32_16x16x32_bf16 v[16:19], v[188:191], v[212:215], v[16:19]
	s_setprio 3
	s_barrier
	v_mfma_f32_16x16x32_bf16 v[8:11], v[174:177], v[220:223], v[8:11]
	v_mfma_f32_16x16x32_bf16 v[0:3], v[188:191], v[220:223], v[0:3]
	s_setprio 0
	v_lshl_add_u64 v[178:179], v[226:227], 0, s[6:7]
	s_mov_b32 m0, s34
	s_nop 0
	s_mov_b64 exec, s[98:99]
	global_load_lds_dwordx4 v[178:179], off
	v_lshl_add_u64 v[178:179], v[228:229], 0, s[6:7]
	s_mov_b32 m0, s35
	s_nop 0
	global_load_lds_dwordx4 v[178:179], off
	s_mov_b64 exec, -1
	s_add_i32 s50, s50, 2
	s_add_u32 s20, s20, 0x100
	s_addc_u32 s21, s21, 0
	s_add_u32 s46, s46, 0x100
	s_addc_u32 s47, s47, 0
	s_cmp_gt_u32 s50, 13
	s_cbranch_scc0 .LBB0_705
	s_and_b64 vcc, exec, s[8:9]
	s_cbranch_vccz .LBB0_708
	s_barrier

.LBB0_776:
	s_add_i32 s39, s39, 1
	s_mul_i32 s4, s39, s73
	s_mul_hi_u32 s5, s39, s72
	s_add_i32 s5, s5, s4
	s_mul_i32 s4, s39, s72
	s_add_u32 s4, s4, s2
	s_addc_u32 s5, s5, s3
	v_cmp_gt_i64_e32 vcc, s[4:5], v[142:143]
	v_cmp_lt_i64_e64 s[6:7], s[4:5], v[140:141]
	s_and_b64 s[98:99], s[6:7], exec
	s_cselect_b32 s100, -1, 0
	s_cbranch_vccnz .LBB0_782
	s_ashr_i32 s5, s4, 31
	s_lshr_b32 s5, s5, 29
	s_add_i32 s16, s4, s5
	s_and_b32 s5, s16, -8
	s_sub_i32 s17, s4, s5
	s_cmp_gt_i32 s17, -1
	s_mov_b64 s[4:5], -1
	s_cbranch_scc0 .LBB0_779
	s_lshl_b32 s22, s17, 6
	s_mov_b64 s[4:5], 0

.LBB0_787:
	ds_read_b128 v[144:147], v151
	ds_read_b128 v[156:159], v151 offset:1024
	ds_read_b128 v[160:163], v151 offset:2048
	ds_read_b128 v[164:167], v151 offset:3072
	ds_read_b128 v[168:171], v152
	ds_read_b128 v[172:175], v152 offset:1024
	ds_read_b128 v[176:179], v152 offset:2048
	ds_read_b128 v[184:187], v152 offset:3072
	s_add_u32 s20, s18, 0x100
	s_addc_u32 s21, s19, 0
	s_cmp_eq_u32 s47, 40
	s_cselect_b32 s25, s7, s21
	s_cselect_b32 s24, s6, s20
	s_cselect_b32 s23, s17, s46
	s_cselect_b32 s22, s16, s43
	s_cselect_b32 s99, 0, -1
	s_or_b32 s99, s99, s100
	s_mov_b32 s98, s99
	v_lshl_add_u64 v[220:221], s[18:19], 0, v[136:137]
	s_add_i32 m0, s29, 0xc000
	ds_read_b128 v[188:191], v153
	ds_read_b128 v[192:195], v153 offset:1024
	ds_read_b128 v[196:199], v153 offset:2048
	ds_read_b128 v[200:203], v153 offset:3072
	ds_read_b128 v[204:207], v153 offset:4096
	ds_read_b128 v[208:211], v153 offset:5120
	ds_read_b128 v[212:215], v153 offset:6144
	ds_read_b128 v[216:219], v153 offset:7168
	global_load_lds_dwordx4 v[220:221], off
	v_lshl_add_u64 v[220:221], s[18:19], 0, v[138:139]
	s_add_i32 m0, s29, 0xe000
	s_nop 0
	global_load_lds_dwordx4 v[220:221], off
	s_waitcnt vmcnt(8)
	s_waitcnt lgkmcnt(0)
	s_barrier
	s_waitcnt lgkmcnt(0)
	v_mfma_f32_16x16x32_bf16 v[124:127], v[144:147], v[188:191], v[124:127]
	v_mfma_f32_16x16x32_bf16 v[120:123], v[160:163], v[188:191], v[120:123]
	v_mfma_f32_16x16x32_bf16 v[108:111], v[144:147], v[196:199], v[108:111]
	v_mfma_f32_16x16x32_bf16 v[104:107], v[160:163], v[196:199], v[104:107]
	v_mfma_f32_16x16x32_bf16 v[92:95], v[144:147], v[204:207], v[92:95]
	v_mfma_f32_16x16x32_bf16 v[88:91], v[160:163], v[204:207], v[88:91]
	v_mfma_f32_16x16x32_bf16 v[76:79], v[144:147], v[212:215], v[76:79]
	v_mfma_f32_16x16x32_bf16 v[72:75], v[160:163], v[212:215], v[72:75]
	v_mfma_f32_16x16x32_bf16 v[124:127], v[156:159], v[192:195], v[124:127]
	v_mfma_f32_16x16x32_bf16 v[120:123], v[164:167], v[192:195], v[120:123]
	v_mfma_f32_16x16x32_bf16 v[108:111], v[156:159], v[200:203], v[108:111]
	v_mfma_f32_16x16x32_bf16 v[104:107], v[164:167], v[200:203], v[104:107]
	v_mfma_f32_16x16x32_bf16 v[92:95], v[156:159], v[208:211], v[92:95]
	v_mfma_f32_16x16x32_bf16 v[88:91], v[164:167], v[208:211], v[88:91]
	v_mfma_f32_16x16x32_bf16 v[76:79], v[156:159], v[216:219], v[76:79]
	v_mfma_f32_16x16x32_bf16 v[72:75], v[164:167], v[216:219], v[72:75]
	v_mfma_f32_16x16x32_bf16 v[116:119], v[168:171], v[188:191], v[116:119]
	v_mfma_f32_16x16x32_bf16 v[112:115], v[176:179], v[188:191], v[112:115]
	v_mfma_f32_16x16x32_bf16 v[100:103], v[168:171], v[196:199], v[100:103]
	v_mfma_f32_16x16x32_bf16 v[96:99], v[176:179], v[196:199], v[96:99]
	v_mfma_f32_16x16x32_bf16 v[84:87], v[168:171], v[204:207], v[84:87]
	v_mfma_f32_16x16x32_bf16 v[80:83], v[176:179], v[204:207], v[80:83]
	v_mfma_f32_16x16x32_bf16 v[68:71], v[168:171], v[212:215], v[68:71]
	v_mfma_f32_16x16x32_bf16 v[64:67], v[176:179], v[212:215], v[64:67]
	v_mfma_f32_16x16x32_bf16 v[116:119], v[172:175], v[192:195], v[116:119]
	v_mfma_f32_16x16x32_bf16 v[112:115], v[184:187], v[192:195], v[112:115]
	v_mfma_f32_16x16x32_bf16 v[100:103], v[172:175], v[200:203], v[100:103]
	v_mfma_f32_16x16x32_bf16 v[96:99], v[184:187], v[200:203], v[96:99]
	v_mfma_f32_16x16x32_bf16 v[84:87], v[172:175], v[208:211], v[84:87]
	v_mfma_f32_16x16x32_bf16 v[80:83], v[184:187], v[208:211], v[80:83]
	s_setprio 3
	s_barrier
	v_mfma_f32_16x16x32_bf16 v[68:71], v[172:175], v[216:219], v[68:71]
	v_mfma_f32_16x16x32_bf16 v[64:67], v[184:187], v[216:219], v[64:67]
	s_setprio 0
	s_add_i32 s18, s37, s28
	v_lshl_add_u64 v[220:221], s[22:23], 0, v[130:131]
	s_mov_b32 m0, s18
	ds_read_b128 v[188:191], v153 offset:16384
	ds_read_b128 v[192:195], v153 offset:17408
	ds_read_b128 v[196:199], v153 offset:18432
	ds_read_b128 v[200:203], v153 offset:19456
	ds_read_b128 v[204:207], v153 offset:20480
	ds_read_b128 v[208:211], v153 offset:21504
	ds_read_b128 v[212:215], v153 offset:22528
	ds_read_b128 v[216:219], v153 offset:23552
	s_mov_b64 exec, s[98:99]
	global_load_lds_dwordx4 v[220:221], off
	s_add_i32 m0, s18, 0x2000
	s_add_u32 s18, s22, 0xb0000
	v_lshl_add_u64 v[222:223], s[22:23], 0, v[134:135]
	s_addc_u32 s19, s23, 0
	s_add_i32 s50, s38, s28
	global_load_lds_dwordx4 v[222:223], off
	v_lshl_add_u64 v[224:225], s[18:19], 0, v[130:131]
	s_mov_b32 m0, s50
	global_load_lds_dwordx4 v[224:225], off
	v_lshl_add_u64 v[224:225], s[18:19], 0, v[134:135]
	s_add_i32 m0, s50, 0x2000
	s_nop 0
	global_load_lds_dwordx4 v[224:225], off
	s_mov_b64 exec, -1
	s_cmp_lg_u32 s99, 0
	s_cbranch_scc1 .Lng_3_1
	s_waitcnt vmcnt(0)
.Lng_3_1:
	s_waitcnt vmcnt(6)
	s_waitcnt lgkmcnt(0)
	s_barrier
	s_waitcnt lgkmcnt(0)
	v_mfma_f32_16x16x32_bf16 v[60:63], v[144:147], v[188:191], v[60:63]
	v_mfma_f32_16x16x32_bf16 v[56:59], v[160:163], v[188:191], v[56:59]
	v_mfma_f32_16x16x32_bf16 v[44:47], v[144:147], v[196:199], v[44:47]
	v_mfma_f32_16x16x32_bf16 v[40:43], v[160:163], v[196:199], v[40:43]
	v_mfma_f32_16x16x32_bf16 v[28:31], v[144:147], v[204:207], v[28:31]
	v_mfma_f32_16x16x32_bf16 v[24:27], v[160:163], v[204:207], v[24:27]
	v_mfma_f32_16x16x32_bf16 v[12:15], v[144:147], v[212:215], v[12:15]
	v_mfma_f32_16x16x32_bf16 v[8:11], v[160:163], v[212:215], v[8:11]
	v_mfma_f32_16x16x32_bf16 v[60:63], v[156:159], v[192:195], v[60:63]
	v_mfma_f32_16x16x32_bf16 v[56:59], v[164:167], v[192:195], v[56:59]
	v_mfma_f32_16x16x32_bf16 v[44:47], v[156:159], v[200:203], v[44:47]
	v_mfma_f32_16x16x32_bf16 v[40:43], v[164:167], v[200:203], v[40:43]
	v_mfma_f32_16x16x32_bf16 v[28:31], v[156:159], v[208:211], v[28:31]
	v_mfma_f32_16x16x32_bf16 v[24:27], v[164:167], v[208:211], v[24:27]
	v_mfma_f32_16x16x32_bf16 v[12:15], v[156:159], v[216:219], v[12:15]
	v_mfma_f32_16x16x32_bf16 v[8:11], v[164:167], v[216:219], v[8:11]
	v_mfma_f32_16x16x32_bf16 v[52:55], v[168:171], v[188:191], v[52:55]
	v_mfma_f32_16x16x32_bf16 v[48:51], v[176:179], v[188:191], v[48:51]
	v_mfma_f32_16x16x32_bf16 v[36:39], v[168:171], v[196:199], v[36:39]
	v_mfma_f32_16x16x32_bf16 v[32:35], v[176:179], v[196:199], v[32:35]
	v_mfma_f32_16x16x32_bf16 v[20:23], v[168:171], v[204:207], v[20:23]
	v_mfma_f32_16x16x32_bf16 v[16:19], v[176:179], v[204:207], v[16:19]
	v_mfma_f32_16x16x32_bf16 v[4:7], v[168:171], v[212:215], v[4:7]
	v_mfma_f32_16x16x32_bf16 v[0:3], v[176:179], v[212:215], v[0:3]
	v_mfma_f32_16x16x32_bf16 v[52:55], v[172:175], v[192:195], v[52:55]
	v_mfma_f32_16x16x32_bf16 v[48:51], v[184:187], v[192:195], v[48:51]
	v_mfma_f32_16x16x32_bf16 v[36:39], v[172:175], v[200:203], v[36:39]
	v_mfma_f32_16x16x32_bf16 v[32:35], v[184:187], v[200:203], v[32:35]
	v_mfma_f32_16x16x32_bf16 v[20:23], v[172:175], v[208:211], v[20:23]
	v_mfma_f32_16x16x32_bf16 v[16:19], v[184:187], v[208:211], v[16:19]
	s_setprio 3
	s_barrier
	v_mfma_f32_16x16x32_bf16 v[4:7], v[172:175], v[216:219], v[4:7]
	v_mfma_f32_16x16x32_bf16 v[0:3], v[184:187], v[216:219], v[0:3]
	s_setprio 0
	s_add_i32 s50, 0, 0x18000
	v_add_u32_e32 v155, s50, v149
	s_add_i32 s51, 0, 0x1c000
	ds_read_b128 v[144:147], v155
	ds_read_b128 v[156:159], v155 offset:1024
	ds_read_b128 v[160:163], v155 offset:2048
	ds_read_b128 v[164:167], v155 offset:3072
	v_add_u32_e32 v155, s51, v149
	ds_read_b128 v[168:171], v155
	ds_read_b128 v[172:175], v155 offset:1024
	ds_read_b128 v[176:179], v155 offset:2048
	ds_read_b128 v[184:187], v155 offset:3072
	s_add_u32 s18, s24, 0xb0000
	s_addc_u32 s19, s25, 0
	v_lshl_add_u64 v[224:225], s[24:25], 0, v[128:129]
	s_mov_b32 m0, s29
	v_lshl_add_u64 v[226:227], s[24:25], 0, v[132:133]
	s_mov_b64 exec, s[98:99]
	global_load_lds_dwordx4 v[224:225], off
	s_mov_b32 m0, s30
	s_nop 0
	global_load_lds_dwordx4 v[226:227], off
	s_mov_b64 exec, -1
	s_mov_b32 m0, s31
	v_lshl_add_u64 v[228:229], s[18:19], 0, v[128:129]
	ds_read_b128 v[188:191], v153 offset:32768
	ds_read_b128 v[192:195], v153 offset:33792
	ds_read_b128 v[196:199], v153 offset:34816
	ds_read_b128 v[200:203], v153 offset:35840
	ds_read_b128 v[204:207], v153 offset:36864
	ds_read_b128 v[208:211], v153 offset:37888
	ds_read_b128 v[212:215], v153 offset:38912
	ds_read_b128 v[216:219], v153 offset:39936
	s_mov_b64 exec, s[98:99]
	global_load_lds_dwordx4 v[228:229], off
	v_lshl_add_u64 v[228:229], s[18:19], 0, v[132:133]
	s_mov_b32 m0, s33
	s_nop 0
	global_load_lds_dwordx4 v[228:229], off
	s_mov_b64 exec, -1
	s_cmp_lg_u32 s99, 0
	s_cbranch_scc1 .Lng_3_2
	s_waitcnt vmcnt(0)
.Lng_3_2:
	s_waitcnt vmcnt(8)
	s_waitcnt lgkmcnt(0)
	s_barrier
	s_waitcnt lgkmcnt(0)
	v_mfma_f32_16x16x32_bf16 v[124:127], v[144:147], v[188:191], v[124:127]
	v_mfma_f32_16x16x32_bf16 v[120:123], v[160:163], v[188:191], v[120:123]
	v_mfma_f32_16x16x32_bf16 v[108:111], v[144:147], v[196:199], v[108:111]
	v_mfma_f32_16x16x32_bf16 v[104:107], v[160:163], v[196:199], v[104:107]
	v_mfma_f32_16x16x32_bf16 v[92:95], v[144:147], v[204:207], v[92:95]
	v_mfma_f32_16x16x32_bf16 v[88:91], v[160:163], v[204:207], v[88:91]
	v_mfma_f32_16x16x32_bf16 v[76:79], v[144:147], v[212:215], v[76:79]
	v_mfma_f32_16x16x32_bf16 v[72:75], v[160:163], v[212:215], v[72:75]
	v_mfma_f32_16x16x32_bf16 v[124:127], v[156:159], v[192:195], v[124:127]
	v_mfma_f32_16x16x32_bf16 v[120:123], v[164:167], v[192:195], v[120:123]
	v_mfma_f32_16x16x32_bf16 v[108:111], v[156:159], v[200:203], v[108:111]
	v_mfma_f32_16x16x32_bf16 v[104:107], v[164:167], v[200:203], v[104:107]
	v_mfma_f32_16x16x32_bf16 v[92:95], v[156:159], v[208:211], v[92:95]
	v_mfma_f32_16x16x32_bf16 v[88:91], v[164:167], v[208:211], v[88:91]
	v_mfma_f32_16x16x32_bf16 v[76:79], v[156:159], v[216:219], v[76:79]
	v_mfma_f32_16x16x32_bf16 v[72:75], v[164:167], v[216:219], v[72:75]
	v_mfma_f32_16x16x32_bf16 v[116:119], v[168:171], v[188:191], v[116:119]
	v_mfma_f32_16x16x32_bf16 v[112:115], v[176:179], v[188:191], v[112:115]
	v_mfma_f32_16x16x32_bf16 v[100:103], v[168:171], v[196:199], v[100:103]
	v_mfma_f32_16x16x32_bf16 v[96:99], v[176:179], v[196:199], v[96:99]
	v_mfma_f32_16x16x32_bf16 v[84:87], v[168:171], v[204:207], v[84:87]
	v_mfma_f32_16x16x32_bf16 v[80:83], v[176:179], v[204:207], v[80:83]
	v_mfma_f32_16x16x32_bf16 v[68:71], v[168:171], v[212:215], v[68:71]
	v_mfma_f32_16x16x32_bf16 v[64:67], v[176:179], v[212:215], v[64:67]
	v_mfma_f32_16x16x32_bf16 v[116:119], v[172:175], v[192:195], v[116:119]
	v_mfma_f32_16x16x32_bf16 v[112:115], v[184:187], v[192:195], v[112:115]
	v_mfma_f32_16x16x32_bf16 v[100:103], v[172:175], v[200:203], v[100:103]
	v_mfma_f32_16x16x32_bf16 v[96:99], v[184:187], v[200:203], v[96:99]
	v_mfma_f32_16x16x32_bf16 v[84:87], v[172:175], v[208:211], v[84:87]
	v_mfma_f32_16x16x32_bf16 v[80:83], v[184:187], v[208:211], v[80:83]
	s_setprio 3
	s_barrier
	v_mfma_f32_16x16x32_bf16 v[68:71], v[172:175], v[216:219], v[68:71]
	v_mfma_f32_16x16x32_bf16 v[64:67], v[184:187], v[216:219], v[64:67]
	s_setprio 0
	s_add_i32 s18, s50, s28
	v_lshl_add_u64 v[220:221], v[220:221], 0, s[12:13]
	s_mov_b32 m0, s18
	ds_read_b128 v[188:191], v153 offset:49152
	ds_read_b128 v[192:195], v153 offset:50176
	ds_read_b128 v[196:199], v153 offset:51200
	ds_read_b128 v[200:203], v153 offset:52224
	ds_read_b128 v[204:207], v153 offset:53248
	ds_read_b128 v[208:211], v153 offset:54272
	ds_read_b128 v[212:215], v153 offset:55296
	ds_read_b128 v[216:219], v153 offset:56320
	s_mov_b64 exec, s[98:99]
	global_load_lds_dwordx4 v[220:221], off
	s_add_i32 m0, s18, 0x2000
	s_add_u32 s18, s22, 0xb0080
	v_lshl_add_u64 v[220:221], v[222:223], 0, s[12:13]
	s_addc_u32 s19, s23, 0
	s_add_i32 s22, s51, s28
	global_load_lds_dwordx4 v[220:221], off
	v_lshl_add_u64 v[220:221], s[18:19], 0, v[130:131]
	s_mov_b32 m0, s22
	s_nop 0
	global_load_lds_dwordx4 v[220:221], off
	v_lshl_add_u64 v[220:221], s[18:19], 0, v[134:135]
	s_add_i32 m0, s22, 0x2000
	s_nop 0
	global_load_lds_dwordx4 v[220:221], off
	s_mov_b64 exec, -1
	s_cmp_lg_u32 s99, 0
	s_cbranch_scc1 .Lng_3_3
	s_waitcnt vmcnt(0)
.Lng_3_3:
	s_waitcnt vmcnt(6)
	s_waitcnt lgkmcnt(0)
	s_barrier
	s_waitcnt lgkmcnt(0)
	v_mfma_f32_16x16x32_bf16 v[60:63], v[144:147], v[188:191], v[60:63]
	v_mfma_f32_16x16x32_bf16 v[56:59], v[160:163], v[188:191], v[56:59]
	v_mfma_f32_16x16x32_bf16 v[44:47], v[144:147], v[196:199], v[44:47]
	v_mfma_f32_16x16x32_bf16 v[40:43], v[160:163], v[196:199], v[40:43]
	v_mfma_f32_16x16x32_bf16 v[28:31], v[144:147], v[204:207], v[28:31]
	v_mfma_f32_16x16x32_bf16 v[24:27], v[160:163], v[204:207], v[24:27]
	v_mfma_f32_16x16x32_bf16 v[12:15], v[144:147], v[212:215], v[12:15]
	v_mfma_f32_16x16x32_bf16 v[8:11], v[160:163], v[212:215], v[8:11]
	v_mfma_f32_16x16x32_bf16 v[60:63], v[156:159], v[192:195], v[60:63]
	v_mfma_f32_16x16x32_bf16 v[56:59], v[164:167], v[192:195], v[56:59]
	v_mfma_f32_16x16x32_bf16 v[44:47], v[156:159], v[200:203], v[44:47]
	v_mfma_f32_16x16x32_bf16 v[40:43], v[164:167], v[200:203], v[40:43]
	v_mfma_f32_16x16x32_bf16 v[28:31], v[156:159], v[208:211], v[28:31]
	v_mfma_f32_16x16x32_bf16 v[24:27], v[164:167], v[208:211], v[24:27]
	v_mfma_f32_16x16x32_bf16 v[12:15], v[156:159], v[216:219], v[12:15]
	v_mfma_f32_16x16x32_bf16 v[8:11], v[164:167], v[216:219], v[8:11]
	v_mfma_f32_16x16x32_bf16 v[52:55], v[168:171], v[188:191], v[52:55]
	v_mfma_f32_16x16x32_bf16 v[48:51], v[176:179], v[188:191], v[48:51]
	v_mfma_f32_16x16x32_bf16 v[36:39], v[168:171], v[196:199], v[36:39]
	v_mfma_f32_16x16x32_bf16 v[32:35], v[176:179], v[196:199], v[32:35]
	v_mfma_f32_16x16x32_bf16 v[20:23], v[168:171], v[204:207], v[20:23]
	v_mfma_f32_16x16x32_bf16 v[16:19], v[176:179], v[204:207], v[16:19]
	v_mfma_f32_16x16x32_bf16 v[4:7], v[168:171], v[212:215], v[4:7]
	v_mfma_f32_16x16x32_bf16 v[0:3], v[176:179], v[212:215], v[0:3]
	v_mfma_f32_16x16x32_bf16 v[52:55], v[172:175], v[192:195], v[52:55]
	v_mfma_f32_16x16x32_bf16 v[48:51], v[184:187], v[192:195], v[48:51]
	v_mfma_f32_16x16x32_bf16 v[36:39], v[172:175], v[200:203], v[36:39]
	v_mfma_f32_16x16x32_bf16 v[32:35], v[184:187], v[200:203], v[32:35]
	v_mfma_f32_16x16x32_bf16 v[20:23], v[172:175], v[208:211], v[20:23]
	v_mfma_f32_16x16x32_bf16 v[16:19], v[184:187], v[208:211], v[16:19]
	s_setprio 3
	s_barrier
	v_mfma_f32_16x16x32_bf16 v[4:7], v[172:175], v[216:219], v[4:7]
	v_mfma_f32_16x16x32_bf16 v[0:3], v[184:187], v[216:219], v[0:3]
	s_setprio 0
	v_lshl_add_u64 v[220:221], v[224:225], 0, s[12:13]
	s_mov_b32 m0, s35
	s_nop 0
	s_mov_b64 exec, s[98:99]
	global_load_lds_dwordx4 v[220:221], off
	v_lshl_add_u64 v[220:221], v[226:227], 0, s[12:13]
	s_mov_b32 m0, s36
	s_nop 0
	global_load_lds_dwordx4 v[220:221], off
	s_mov_b64 exec, -1
	s_add_i32 s47, s47, 2
	s_add_u32 s43, s43, 0x100
	s_addc_u32 s46, s46, 0
	s_cmp_gt_u32 s47, 41
	s_mov_b64 s[18:19], s[20:21]
	s_cbranch_scc0 .LBB0_787
	s_and_b64 vcc, exec, s[14:15]
	s_cbranch_vccz .LBB0_790
	s_barrier

.LBB0_874:
	s_add_i32 s52, s9, 1
	s_mul_i32 s6, s52, s73
	s_mul_hi_u32 s7, s52, s72
	s_add_i32 s7, s7, s6
	s_mul_i32 s6, s52, s72
	s_add_u32 s24, s6, s2
	s_addc_u32 s25, s7, s3
	v_cmp_gt_i64_e32 vcc, s[24:25], v[142:143]
	v_cmp_lt_i64_e64 s[6:7], s[24:25], v[140:141]
	s_and_b64 s[98:99], s[6:7], exec
	s_cselect_b32 s100, -1, 0
	s_cbranch_vccnz .LBB0_876
	s_ashr_i32 s11, s24, 31
	s_lshr_b32 s11, s11, 29
	s_add_i32 s11, s24, s11
	s_ashr_i32 s20, s11, 3
	s_and_b32 s11, s11, -8
	s_sub_i32 s11, s24, s11
	s_cmp_lt_i32 s11, 0
	s_cselect_b32 s21, s46, 0xa0
	s_mul_i32 s11, s21, s11
	s_add_i32 s11, s11, s20
	s_mul_hi_i32 s20, s11, 0x66666667
	s_lshr_b32 s21, s20, 31
	s_ashr_i32 s20, s20, 5
	s_add_i32 s20, s20, s21
	s_lshl_b32 s21, s20, 3
	s_sub_i32 s22, 0x80, s21
	s_min_i32 s22, s22, 8
	s_abs_i32 s23, s22
	v_cvt_f32_u32_e32 v0, s23
	s_sub_i32 s25, 0, s23
	s_mulk_i32 s20, 0x50
	s_sub_i32 s11, s11, s20
	v_rcp_iflag_f32_e32 v0, v0
	s_abs_i32 s20, s11
	s_xor_b32 s24, s11, s22
	s_ashr_i32 s24, s24, 31
	v_mul_f32_e32 v0, 0x4f7ffffe, v0
	v_cvt_u32_f32_e32 v0, v0
	s_nop 0
	v_readfirstlane_b32 s26, v0
	s_mul_i32 s25, s25, s26
	s_mul_hi_u32 s25, s26, s25
	s_add_i32 s26, s26, s25
	s_mul_hi_u32 s25, s20, s26
	s_mul_i32 s26, s25, s23
	s_sub_i32 s20, s20, s26
	s_add_i32 s27, s25, 1
	s_sub_i32 s26, s20, s23
	s_cmp_ge_u32 s20, s23
	s_cselect_b32 s25, s27, s25
	s_cselect_b32 s20, s26, s20
	s_add_i32 s26, s25, 1
	s_cmp_ge_u32 s20, s23
	s_cselect_b32 s20, s26, s25
	s_xor_b32 s20, s20, s24
	s_sub_i32 s20, s20, s24
	s_mul_i32 s22, s20, s22
	s_sub_i32 s11, s11, s22
	s_add_i32 s22, s11, s21

.LBB0_877:
	ds_read_b128 v[144:147], v173
	ds_read_b128 v[148:151], v173 offset:1024
	ds_read_b128 v[152:155], v173 offset:2048
	ds_read_b128 v[156:159], v173 offset:3072
	ds_read_b128 v[184:187], v174
	ds_read_b128 v[188:191], v174 offset:1024
	ds_read_b128 v[192:195], v174 offset:2048
	ds_read_b128 v[196:199], v174 offset:3072
	s_add_u32 s30, s28, 0xfffc0080
	s_addc_u32 s31, s29, -1
	s_cmp_eq_u32 s56, 12
	s_cselect_b32 s35, s11, s31
	s_cselect_b32 s34, s23, s30
	s_cselect_b32 s31, s21, s55
	s_cselect_b32 s30, s53, s54
	s_cselect_b32 s99, 0, -1
	s_or_b32 s99, s99, s100
	s_mov_b32 s98, s99
	v_lshl_add_u64 v[160:161], s[28:29], 0, v[136:137]
	s_add_i32 m0, s38, 0xc000
	ds_read_b128 v[200:203], v175
	ds_read_b128 v[204:207], v175 offset:1024
	ds_read_b128 v[208:211], v175 offset:2048
	ds_read_b128 v[212:215], v175 offset:3072
	ds_read_b128 v[216:219], v175 offset:4096
	ds_read_b128 v[220:223], v175 offset:5120
	ds_read_b128 v[224:227], v175 offset:6144
	ds_read_b128 v[228:231], v175 offset:7168
	global_load_lds_dwordx4 v[160:161], off
	v_lshl_add_u64 v[160:161], s[28:29], 0, v[138:139]
	s_add_i32 m0, s38, 0xe000
	s_nop 0
	global_load_lds_dwordx4 v[160:161], off
	s_waitcnt vmcnt(8)
	s_waitcnt lgkmcnt(0)
	s_barrier
	s_waitcnt lgkmcnt(0)
	v_mfma_f32_16x16x32_bf16 v[124:127], v[144:147], v[200:203], v[124:127]
	v_mfma_f32_16x16x32_bf16 v[120:123], v[152:155], v[200:203], v[120:123]
	v_mfma_f32_16x16x32_bf16 v[108:111], v[144:147], v[208:211], v[108:111]
	v_mfma_f32_16x16x32_bf16 v[104:107], v[152:155], v[208:211], v[104:107]
	v_mfma_f32_16x16x32_bf16 v[92:95], v[144:147], v[216:219], v[92:95]
	v_mfma_f32_16x16x32_bf16 v[88:91], v[152:155], v[216:219], v[88:91]
	v_mfma_f32_16x16x32_bf16 v[76:79], v[144:147], v[224:227], v[76:79]
	v_mfma_f32_16x16x32_bf16 v[72:75], v[152:155], v[224:227], v[72:75]
	v_mfma_f32_16x16x32_bf16 v[124:127], v[148:151], v[204:207], v[124:127]
	v_mfma_f32_16x16x32_bf16 v[120:123], v[156:159], v[204:207], v[120:123]
	v_mfma_f32_16x16x32_bf16 v[108:111], v[148:151], v[212:215], v[108:111]
	v_mfma_f32_16x16x32_bf16 v[104:107], v[156:159], v[212:215], v[104:107]
	v_mfma_f32_16x16x32_bf16 v[92:95], v[148:151], v[220:223], v[92:95]
	v_mfma_f32_16x16x32_bf16 v[88:91], v[156:159], v[220:223], v[88:91]
	v_mfma_f32_16x16x32_bf16 v[76:79], v[148:151], v[228:231], v[76:79]
	v_mfma_f32_16x16x32_bf16 v[72:75], v[156:159], v[228:231], v[72:75]
	v_mfma_f32_16x16x32_bf16 v[116:119], v[184:187], v[200:203], v[116:119]
	v_mfma_f32_16x16x32_bf16 v[112:115], v[192:195], v[200:203], v[112:115]
	v_mfma_f32_16x16x32_bf16 v[100:103], v[184:187], v[208:211], v[100:103]
	v_mfma_f32_16x16x32_bf16 v[96:99], v[192:195], v[208:211], v[96:99]
	v_mfma_f32_16x16x32_bf16 v[84:87], v[184:187], v[216:219], v[84:87]
	v_mfma_f32_16x16x32_bf16 v[80:83], v[192:195], v[216:219], v[80:83]
	v_mfma_f32_16x16x32_bf16 v[68:71], v[184:187], v[224:227], v[68:71]
	v_mfma_f32_16x16x32_bf16 v[64:67], v[192:195], v[224:227], v[64:67]
	v_mfma_f32_16x16x32_bf16 v[116:119], v[188:191], v[204:207], v[116:119]
	v_mfma_f32_16x16x32_bf16 v[112:115], v[196:199], v[204:207], v[112:115]
	v_mfma_f32_16x16x32_bf16 v[100:103], v[188:191], v[212:215], v[100:103]
	v_mfma_f32_16x16x32_bf16 v[96:99], v[196:199], v[212:215], v[96:99]
	v_mfma_f32_16x16x32_bf16 v[84:87], v[188:191], v[220:223], v[84:87]
	v_mfma_f32_16x16x32_bf16 v[80:83], v[196:199], v[220:223], v[80:83]
	s_setprio 3
	s_barrier
	v_mfma_f32_16x16x32_bf16 v[68:71], v[188:191], v[228:231], v[68:71]
	v_mfma_f32_16x16x32_bf16 v[64:67], v[196:199], v[228:231], v[64:67]
	s_setprio 0
	s_add_i32 s57, s47, s37
	v_lshl_add_u64 v[160:161], s[30:31], 0, v[130:131]
	s_mov_b32 m0, s57
	ds_read_b128 v[200:203], v175 offset:16384
	ds_read_b128 v[204:207], v175 offset:17408
	ds_read_b128 v[208:211], v175 offset:18432
	ds_read_b128 v[212:215], v175 offset:19456
	ds_read_b128 v[216:219], v175 offset:20480
	ds_read_b128 v[220:223], v175 offset:21504
	ds_read_b128 v[224:227], v175 offset:22528
	ds_read_b128 v[228:231], v175 offset:23552
	s_mov_b64 exec, s[98:99]
	global_load_lds_dwordx4 v[160:161], off
	s_add_i32 m0, s57, 0x2000
	s_add_u32 s58, s30, 0x40000
	v_lshl_add_u64 v[178:179], s[30:31], 0, v[134:135]
	s_addc_u32 s59, s31, 0
	s_add_i32 s57, s50, s37
	global_load_lds_dwordx4 v[178:179], off
	v_lshl_add_u64 v[232:233], s[58:59], 0, v[130:131]
	s_mov_b32 m0, s57
	global_load_lds_dwordx4 v[232:233], off
	v_lshl_add_u64 v[232:233], s[58:59], 0, v[134:135]
	s_add_i32 m0, s57, 0x2000
	s_nop 0
	global_load_lds_dwordx4 v[232:233], off
	s_mov_b64 exec, -1
	s_cmp_lg_u32 s99, 0
	s_cbranch_scc1 .Lng_4_1
	s_waitcnt vmcnt(0)
.Lng_4_1:
	s_waitcnt vmcnt(6)
	s_waitcnt lgkmcnt(0)
	s_barrier
	s_waitcnt lgkmcnt(0)
	v_mfma_f32_16x16x32_bf16 v[60:63], v[144:147], v[200:203], v[60:63]
	v_mfma_f32_16x16x32_bf16 v[56:59], v[152:155], v[200:203], v[56:59]
	v_mfma_f32_16x16x32_bf16 v[44:47], v[144:147], v[208:211], v[44:47]
	v_mfma_f32_16x16x32_bf16 v[40:43], v[152:155], v[208:211], v[40:43]
	v_mfma_f32_16x16x32_bf16 v[28:31], v[144:147], v[216:219], v[28:31]
	v_mfma_f32_16x16x32_bf16 v[24:27], v[152:155], v[216:219], v[24:27]
	v_mfma_f32_16x16x32_bf16 v[12:15], v[144:147], v[224:227], v[12:15]
	v_mfma_f32_16x16x32_bf16 v[8:11], v[152:155], v[224:227], v[8:11]
	v_mfma_f32_16x16x32_bf16 v[60:63], v[148:151], v[204:207], v[60:63]
	v_mfma_f32_16x16x32_bf16 v[56:59], v[156:159], v[204:207], v[56:59]
	v_mfma_f32_16x16x32_bf16 v[44:47], v[148:151], v[212:215], v[44:47]
	v_mfma_f32_16x16x32_bf16 v[40:43], v[156:159], v[212:215], v[40:43]
	v_mfma_f32_16x16x32_bf16 v[28:31], v[148:151], v[220:223], v[28:31]
	v_mfma_f32_16x16x32_bf16 v[24:27], v[156:159], v[220:223], v[24:27]
	v_mfma_f32_16x16x32_bf16 v[12:15], v[148:151], v[228:231], v[12:15]
	v_mfma_f32_16x16x32_bf16 v[8:11], v[156:159], v[228:231], v[8:11]
	v_mfma_f32_16x16x32_bf16 v[52:55], v[184:187], v[200:203], v[52:55]
	v_mfma_f32_16x16x32_bf16 v[48:51], v[192:195], v[200:203], v[48:51]
	v_mfma_f32_16x16x32_bf16 v[36:39], v[184:187], v[208:211], v[36:39]
	v_mfma_f32_16x16x32_bf16 v[32:35], v[192:195], v[208:211], v[32:35]
	v_mfma_f32_16x16x32_bf16 v[20:23], v[184:187], v[216:219], v[20:23]
	v_mfma_f32_16x16x32_bf16 v[16:19], v[192:195], v[216:219], v[16:19]
	v_mfma_f32_16x16x32_bf16 v[4:7], v[184:187], v[224:227], v[4:7]
	v_mfma_f32_16x16x32_bf16 v[0:3], v[192:195], v[224:227], v[0:3]
	v_mfma_f32_16x16x32_bf16 v[52:55], v[188:191], v[204:207], v[52:55]
	v_mfma_f32_16x16x32_bf16 v[48:51], v[196:199], v[204:207], v[48:51]
	v_mfma_f32_16x16x32_bf16 v[36:39], v[188:191], v[212:215], v[36:39]
	v_mfma_f32_16x16x32_bf16 v[32:35], v[196:199], v[212:215], v[32:35]
	v_mfma_f32_16x16x32_bf16 v[20:23], v[188:191], v[220:223], v[20:23]
	v_mfma_f32_16x16x32_bf16 v[16:19], v[196:199], v[220:223], v[16:19]
	s_setprio 3
	s_barrier
	v_mfma_f32_16x16x32_bf16 v[4:7], v[188:191], v[228:231], v[4:7]
	v_mfma_f32_16x16x32_bf16 v[0:3], v[196:199], v[228:231], v[0:3]
	s_setprio 0
	s_add_i32 s57, 0, 0x18000
	s_add_i32 s58, 0, 0x1c000
	v_add_u32_e32 v156, s57, v163
	v_add_u32_e32 v177, s58, v163
	ds_read_b128 v[144:147], v156
	ds_read_b128 v[148:151], v156 offset:1024
	ds_read_b128 v[152:155], v156 offset:2048
	ds_read_b128 v[156:159], v156 offset:3072
	ds_read_b128 v[184:187], v177
	ds_read_b128 v[188:191], v177 offset:1024
	ds_read_b128 v[192:195], v177 offset:2048
	ds_read_b128 v[196:199], v177 offset:3072
	v_lshl_add_u64 v[232:233], s[34:35], 0, v[128:129]
	s_mov_b32 m0, s38
	v_lshl_add_u64 v[234:235], s[34:35], 0, v[132:133]
	s_mov_b64 exec, s[98:99]
	global_load_lds_dwordx4 v[232:233], off
	s_mov_b32 m0, s39
	s_nop 0
	global_load_lds_dwordx4 v[234:235], off
	s_mov_b64 exec, -1
	s_add_u32 s34, s34, 0x40000
	s_addc_u32 s35, s35, 0
	s_mov_b32 m0, s40
	v_lshl_add_u64 v[236:237], s[34:35], 0, v[128:129]
	ds_read_b128 v[200:203], v175 offset:32768
	ds_read_b128 v[204:207], v175 offset:33792
	ds_read_b128 v[208:211], v175 offset:34816
	ds_read_b128 v[212:215], v175 offset:35840
	ds_read_b128 v[216:219], v175 offset:36864
	ds_read_b128 v[220:223], v175 offset:37888
	ds_read_b128 v[224:227], v175 offset:38912
	ds_read_b128 v[228:231], v175 offset:39936
	s_mov_b64 exec, s[98:99]
	global_load_lds_dwordx4 v[236:237], off
	v_lshl_add_u64 v[236:237], s[34:35], 0, v[132:133]
	s_mov_b32 m0, s41
	s_nop 0
	global_load_lds_dwordx4 v[236:237], off
	s_mov_b64 exec, -1
	s_cmp_lg_u32 s99, 0
	s_cbranch_scc1 .Lng_4_2
	s_waitcnt vmcnt(0)
.Lng_4_2:
	s_waitcnt vmcnt(8)
	s_waitcnt lgkmcnt(0)
	s_barrier
	s_waitcnt lgkmcnt(0)
	v_mfma_f32_16x16x32_bf16 v[124:127], v[144:147], v[200:203], v[124:127]
	v_mfma_f32_16x16x32_bf16 v[120:123], v[152:155], v[200:203], v[120:123]
	v_mfma_f32_16x16x32_bf16 v[108:111], v[144:147], v[208:211], v[108:111]
	v_mfma_f32_16x16x32_bf16 v[104:107], v[152:155], v[208:211], v[104:107]
	v_mfma_f32_16x16x32_bf16 v[92:95], v[144:147], v[216:219], v[92:95]
	v_mfma_f32_16x16x32_bf16 v[88:91], v[152:155], v[216:219], v[88:91]
	v_mfma_f32_16x16x32_bf16 v[76:79], v[144:147], v[224:227], v[76:79]
	v_mfma_f32_16x16x32_bf16 v[72:75], v[152:155], v[224:227], v[72:75]
	v_mfma_f32_16x16x32_bf16 v[124:127], v[148:151], v[204:207], v[124:127]
	v_mfma_f32_16x16x32_bf16 v[120:123], v[156:159], v[204:207], v[120:123]
	v_mfma_f32_16x16x32_bf16 v[108:111], v[148:151], v[212:215], v[108:111]
	v_mfma_f32_16x16x32_bf16 v[104:107], v[156:159], v[212:215], v[104:107]
	v_mfma_f32_16x16x32_bf16 v[92:95], v[148:151], v[220:223], v[92:95]
	v_mfma_f32_16x16x32_bf16 v[88:91], v[156:159], v[220:223], v[88:91]
	v_mfma_f32_16x16x32_bf16 v[76:79], v[148:151], v[228:231], v[76:79]
	v_mfma_f32_16x16x32_bf16 v[72:75], v[156:159], v[228:231], v[72:75]
	v_mfma_f32_16x16x32_bf16 v[116:119], v[184:187], v[200:203], v[116:119]
	v_mfma_f32_16x16x32_bf16 v[112:115], v[192:195], v[200:203], v[112:115]
	v_mfma_f32_16x16x32_bf16 v[100:103], v[184:187], v[208:211], v[100:103]
	v_mfma_f32_16x16x32_bf16 v[96:99], v[192:195], v[208:211], v[96:99]
	v_mfma_f32_16x16x32_bf16 v[84:87], v[184:187], v[216:219], v[84:87]
	v_mfma_f32_16x16x32_bf16 v[80:83], v[192:195], v[216:219], v[80:83]
	v_mfma_f32_16x16x32_bf16 v[68:71], v[184:187], v[224:227], v[68:71]
	v_mfma_f32_16x16x32_bf16 v[64:67], v[192:195], v[224:227], v[64:67]
	v_mfma_f32_16x16x32_bf16 v[116:119], v[188:191], v[204:207], v[116:119]
	v_mfma_f32_16x16x32_bf16 v[112:115], v[196:199], v[204:207], v[112:115]
	v_mfma_f32_16x16x32_bf16 v[100:103], v[188:191], v[212:215], v[100:103]
	v_mfma_f32_16x16x32_bf16 v[96:99], v[196:199], v[212:215], v[96:99]
	v_mfma_f32_16x16x32_bf16 v[84:87], v[188:191], v[220:223], v[84:87]
	v_mfma_f32_16x16x32_bf16 v[80:83], v[196:199], v[220:223], v[80:83]
	s_setprio 3
	s_barrier
	v_mfma_f32_16x16x32_bf16 v[68:71], v[188:191], v[228:231], v[68:71]
	v_mfma_f32_16x16x32_bf16 v[64:67], v[196:199], v[228:231], v[64:67]
	s_setprio 0
	s_add_i32 s34, s57, s37
	v_lshl_add_u64 v[160:161], v[160:161], 0, s[14:15]
	s_mov_b32 m0, s34
	ds_read_b128 v[200:203], v175 offset:49152
	ds_read_b128 v[204:207], v175 offset:50176
	ds_read_b128 v[208:211], v175 offset:51200
	ds_read_b128 v[212:215], v175 offset:52224
	ds_read_b128 v[216:219], v175 offset:53248
	ds_read_b128 v[220:223], v175 offset:54272
	ds_read_b128 v[224:227], v175 offset:55296
	ds_read_b128 v[228:231], v175 offset:56320
	s_mov_b64 exec, s[98:99]
	global_load_lds_dwordx4 v[160:161], off
	s_add_i32 m0, s34, 0x2000
	s_add_u32 s30, s30, 0x40080
	v_lshl_add_u64 v[160:161], v[178:179], 0, s[14:15]
	s_addc_u32 s31, s31, 0
	s_add_i32 s34, s58, s37
	global_load_lds_dwordx4 v[160:161], off
	v_lshl_add_u64 v[160:161], s[30:31], 0, v[130:131]
	s_mov_b32 m0, s34
	s_nop 0
	global_load_lds_dwordx4 v[160:161], off
	v_lshl_add_u64 v[160:161], s[30:31], 0, v[134:135]
	s_add_i32 m0, s34, 0x2000
	s_nop 0
	global_load_lds_dwordx4 v[160:161], off
	s_mov_b64 exec, -1
	s_cmp_lg_u32 s99, 0
	s_cbranch_scc1 .Lng_4_3
	s_waitcnt vmcnt(0)
.Lng_4_3:
	s_waitcnt vmcnt(6)
	s_waitcnt lgkmcnt(0)
	s_barrier
	s_waitcnt lgkmcnt(0)
	v_mfma_f32_16x16x32_bf16 v[60:63], v[144:147], v[200:203], v[60:63]
	v_mfma_f32_16x16x32_bf16 v[56:59], v[152:155], v[200:203], v[56:59]
	v_mfma_f32_16x16x32_bf16 v[44:47], v[144:147], v[208:211], v[44:47]
	v_mfma_f32_16x16x32_bf16 v[40:43], v[152:155], v[208:211], v[40:43]
	v_mfma_f32_16x16x32_bf16 v[28:31], v[144:147], v[216:219], v[28:31]
	v_mfma_f32_16x16x32_bf16 v[24:27], v[152:155], v[216:219], v[24:27]
	v_mfma_f32_16x16x32_bf16 v[12:15], v[144:147], v[224:227], v[12:15]
	v_mfma_f32_16x16x32_bf16 v[8:11], v[152:155], v[224:227], v[8:11]
	v_mfma_f32_16x16x32_bf16 v[60:63], v[148:151], v[204:207], v[60:63]
	v_mfma_f32_16x16x32_bf16 v[56:59], v[156:159], v[204:207], v[56:59]
	v_mfma_f32_16x16x32_bf16 v[44:47], v[148:151], v[212:215], v[44:47]
	v_mfma_f32_16x16x32_bf16 v[40:43], v[156:159], v[212:215], v[40:43]
	v_mfma_f32_16x16x32_bf16 v[28:31], v[148:151], v[220:223], v[28:31]
	v_mfma_f32_16x16x32_bf16 v[24:27], v[156:159], v[220:223], v[24:27]
	v_mfma_f32_16x16x32_bf16 v[12:15], v[148:151], v[228:231], v[12:15]
	v_mfma_f32_16x16x32_bf16 v[8:11], v[156:159], v[228:231], v[8:11]
	v_mfma_f32_16x16x32_bf16 v[52:55], v[184:187], v[200:203], v[52:55]
	v_mfma_f32_16x16x32_bf16 v[48:51], v[192:195], v[200:203], v[48:51]
	v_mfma_f32_16x16x32_bf16 v[36:39], v[184:187], v[208:211], v[36:39]
	v_mfma_f32_16x16x32_bf16 v[32:35], v[192:195], v[208:211], v[32:35]
	v_mfma_f32_16x16x32_bf16 v[20:23], v[184:187], v[216:219], v[20:23]
	v_mfma_f32_16x16x32_bf16 v[16:19], v[192:195], v[216:219], v[16:19]
	v_mfma_f32_16x16x32_bf16 v[4:7], v[184:187], v[224:227], v[4:7]
	v_mfma_f32_16x16x32_bf16 v[0:3], v[192:195], v[224:227], v[0:3]
	v_mfma_f32_16x16x32_bf16 v[52:55], v[188:191], v[204:207], v[52:55]
	v_mfma_f32_16x16x32_bf16 v[48:51], v[196:199], v[204:207], v[48:51]
	v_mfma_f32_16x16x32_bf16 v[36:39], v[188:191], v[212:215], v[36:39]
	v_mfma_f32_16x16x32_bf16 v[32:35], v[196:199], v[212:215], v[32:35]
	v_mfma_f32_16x16x32_bf16 v[20:23], v[188:191], v[220:223], v[20:23]
	v_mfma_f32_16x16x32_bf16 v[16:19], v[196:199], v[220:223], v[16:19]
	s_setprio 3
	s_barrier
	v_mfma_f32_16x16x32_bf16 v[4:7], v[188:191], v[228:231], v[4:7]
	v_mfma_f32_16x16x32_bf16 v[0:3], v[196:199], v[228:231], v[0:3]
	s_setprio 0
	v_lshl_add_u64 v[160:161], v[232:233], 0, s[14:15]
	s_mov_b32 m0, s42
	s_nop 0
	s_mov_b64 exec, s[98:99]
	global_load_lds_dwordx4 v[160:161], off
	v_lshl_add_u64 v[160:161], v[234:235], 0, s[14:15]
	s_mov_b32 m0, s43
	s_nop 0
	global_load_lds_dwordx4 v[160:161], off
	s_mov_b64 exec, -1
	s_add_i32 s56, s56, 2
	s_add_u32 s28, s28, 0x100
	s_addc_u32 s29, s29, 0
	s_add_u32 s54, s54, 0x100
	s_addc_u32 s55, s55, 0
	s_cmp_gt_u32 s56, 13
	s_cbranch_scc0 .LBB0_877
	s_and_b64 vcc, exec, s[16:17]
	s_cbranch_vccz .LBB0_880
	s_barrier

.LBB0_1291:
	ds_read_b128 v[144:147], v151
	ds_read_b128 v[156:159], v151 offset:1024
	ds_read_b128 v[160:163], v151 offset:2048
	ds_read_b128 v[164:167], v151 offset:3072
	ds_read_b128 v[168:171], v152
	ds_read_b128 v[172:175], v152 offset:1024
	ds_read_b128 v[176:179], v152 offset:2048
	ds_read_b128 v[184:187], v152 offset:3072
	s_add_u32 s26, s24, 0xfffc0080
	s_addc_u32 s27, s25, -1
	s_cmp_eq_u32 s47, 12
	s_cselect_b32 s29, s17, s27
	s_cselect_b32 s28, s23, s26
	s_cselect_b32 s27, s15, s46
	s_cselect_b32 s26, s44, s45
	s_cselect_b32 s99, 0, -1
	s_or_b32 s99, s99, s100
	s_mov_b32 s98, s99
	v_lshl_add_u64 v[220:221], s[24:25], 0, v[136:137]
	s_add_i32 m0, s34, 0xc000
	ds_read_b128 v[188:191], v153
	ds_read_b128 v[192:195], v153 offset:1024
	ds_read_b128 v[196:199], v153 offset:2048
	ds_read_b128 v[200:203], v153 offset:3072
	ds_read_b128 v[204:207], v153 offset:4096
	ds_read_b128 v[208:211], v153 offset:5120
	ds_read_b128 v[212:215], v153 offset:6144
	ds_read_b128 v[216:219], v153 offset:7168
	global_load_lds_dwordx4 v[220:221], off
	v_lshl_add_u64 v[220:221], s[24:25], 0, v[138:139]
	s_add_i32 m0, s34, 0xe000
	s_nop 0
	global_load_lds_dwordx4 v[220:221], off
	s_waitcnt vmcnt(8)
	s_waitcnt lgkmcnt(0)
	s_barrier
	s_waitcnt lgkmcnt(0)
	v_mfma_f32_16x16x32_bf16 v[124:127], v[144:147], v[188:191], v[124:127]
	v_mfma_f32_16x16x32_bf16 v[120:123], v[160:163], v[188:191], v[120:123]
	v_mfma_f32_16x16x32_bf16 v[108:111], v[144:147], v[196:199], v[108:111]
	v_mfma_f32_16x16x32_bf16 v[104:107], v[160:163], v[196:199], v[104:107]
	v_mfma_f32_16x16x32_bf16 v[92:95], v[144:147], v[204:207], v[92:95]
	v_mfma_f32_16x16x32_bf16 v[88:91], v[160:163], v[204:207], v[88:91]
	v_mfma_f32_16x16x32_bf16 v[76:79], v[144:147], v[212:215], v[76:79]
	v_mfma_f32_16x16x32_bf16 v[72:75], v[160:163], v[212:215], v[72:75]
	v_mfma_f32_16x16x32_bf16 v[124:127], v[156:159], v[192:195], v[124:127]
	v_mfma_f32_16x16x32_bf16 v[120:123], v[164:167], v[192:195], v[120:123]
	v_mfma_f32_16x16x32_bf16 v[108:111], v[156:159], v[200:203], v[108:111]
	v_mfma_f32_16x16x32_bf16 v[104:107], v[164:167], v[200:203], v[104:107]
	v_mfma_f32_16x16x32_bf16 v[92:95], v[156:159], v[208:211], v[92:95]
	v_mfma_f32_16x16x32_bf16 v[88:91], v[164:167], v[208:211], v[88:91]
	v_mfma_f32_16x16x32_bf16 v[76:79], v[156:159], v[216:219], v[76:79]
	v_mfma_f32_16x16x32_bf16 v[72:75], v[164:167], v[216:219], v[72:75]
	v_mfma_f32_16x16x32_bf16 v[116:119], v[168:171], v[188:191], v[116:119]
	v_mfma_f32_16x16x32_bf16 v[112:115], v[176:179], v[188:191], v[112:115]
	v_mfma_f32_16x16x32_bf16 v[100:103], v[168:171], v[196:199], v[100:103]
	v_mfma_f32_16x16x32_bf16 v[96:99], v[176:179], v[196:199], v[96:99]
	v_mfma_f32_16x16x32_bf16 v[84:87], v[168:171], v[204:207], v[84:87]
	v_mfma_f32_16x16x32_bf16 v[80:83], v[176:179], v[204:207], v[80:83]
	v_mfma_f32_16x16x32_bf16 v[68:71], v[168:171], v[212:215], v[68:71]
	v_mfma_f32_16x16x32_bf16 v[64:67], v[176:179], v[212:215], v[64:67]
	v_mfma_f32_16x16x32_bf16 v[116:119], v[172:175], v[192:195], v[116:119]
	v_mfma_f32_16x16x32_bf16 v[112:115], v[184:187], v[192:195], v[112:115]
	v_mfma_f32_16x16x32_bf16 v[100:103], v[172:175], v[200:203], v[100:103]
	v_mfma_f32_16x16x32_bf16 v[96:99], v[184:187], v[200:203], v[96:99]
	v_mfma_f32_16x16x32_bf16 v[84:87], v[172:175], v[208:211], v[84:87]
	v_mfma_f32_16x16x32_bf16 v[80:83], v[184:187], v[208:211], v[80:83]
	s_setprio 3
	s_barrier
	v_mfma_f32_16x16x32_bf16 v[68:71], v[172:175], v[216:219], v[68:71]
	v_mfma_f32_16x16x32_bf16 v[64:67], v[184:187], v[216:219], v[64:67]
	s_setprio 0
	s_add_i32 s50, s41, s33
	v_lshl_add_u64 v[220:221], s[26:27], 0, v[130:131]
	s_mov_b32 m0, s50
	ds_read_b128 v[188:191], v153 offset:16384
	ds_read_b128 v[192:195], v153 offset:17408
	ds_read_b128 v[196:199], v153 offset:18432
	ds_read_b128 v[200:203], v153 offset:19456
	ds_read_b128 v[204:207], v153 offset:20480
	ds_read_b128 v[208:211], v153 offset:21504
	ds_read_b128 v[212:215], v153 offset:22528
	ds_read_b128 v[216:219], v153 offset:23552
	s_mov_b64 exec, s[98:99]
	global_load_lds_dwordx4 v[220:221], off
	s_add_i32 m0, s50, 0x2000
	s_add_u32 s50, s26, 0x40000
	v_lshl_add_u64 v[222:223], s[26:27], 0, v[134:135]
	s_addc_u32 s51, s27, 0
	s_add_i32 s52, s42, s33
	global_load_lds_dwordx4 v[222:223], off
	v_lshl_add_u64 v[224:225], s[50:51], 0, v[130:131]
	s_mov_b32 m0, s52
	global_load_lds_dwordx4 v[224:225], off
	v_lshl_add_u64 v[224:225], s[50:51], 0, v[134:135]
	s_add_i32 m0, s52, 0x2000
	s_nop 0
	global_load_lds_dwordx4 v[224:225], off
	s_mov_b64 exec, -1
	s_cmp_lg_u32 s99, 0
	s_cbranch_scc1 .Lng_5_1
	s_waitcnt vmcnt(0)
.Lng_5_1:
	s_waitcnt vmcnt(6)
	s_waitcnt lgkmcnt(0)
	s_barrier
	s_waitcnt lgkmcnt(0)
	v_mfma_f32_16x16x32_bf16 v[60:63], v[144:147], v[188:191], v[60:63]
	v_mfma_f32_16x16x32_bf16 v[56:59], v[160:163], v[188:191], v[56:59]
	v_mfma_f32_16x16x32_bf16 v[44:47], v[144:147], v[196:199], v[44:47]
	v_mfma_f32_16x16x32_bf16 v[40:43], v[160:163], v[196:199], v[40:43]
	v_mfma_f32_16x16x32_bf16 v[28:31], v[144:147], v[204:207], v[28:31]
	v_mfma_f32_16x16x32_bf16 v[24:27], v[160:163], v[204:207], v[24:27]
	v_mfma_f32_16x16x32_bf16 v[12:15], v[144:147], v[212:215], v[12:15]
	v_mfma_f32_16x16x32_bf16 v[8:11], v[160:163], v[212:215], v[8:11]
	v_mfma_f32_16x16x32_bf16 v[60:63], v[156:159], v[192:195], v[60:63]
	v_mfma_f32_16x16x32_bf16 v[56:59], v[164:167], v[192:195], v[56:59]
	v_mfma_f32_16x16x32_bf16 v[44:47], v[156:159], v[200:203], v[44:47]
	v_mfma_f32_16x16x32_bf16 v[40:43], v[164:167], v[200:203], v[40:43]
	v_mfma_f32_16x16x32_bf16 v[28:31], v[156:159], v[208:211], v[28:31]
	v_mfma_f32_16x16x32_bf16 v[24:27], v[164:167], v[208:211], v[24:27]
	v_mfma_f32_16x16x32_bf16 v[12:15], v[156:159], v[216:219], v[12:15]
	v_mfma_f32_16x16x32_bf16 v[8:11], v[164:167], v[216:219], v[8:11]
	v_mfma_f32_16x16x32_bf16 v[52:55], v[168:171], v[188:191], v[52:55]
	v_mfma_f32_16x16x32_bf16 v[48:51], v[176:179], v[188:191], v[48:51]
	v_mfma_f32_16x16x32_bf16 v[36:39], v[168:171], v[196:199], v[36:39]
	v_mfma_f32_16x16x32_bf16 v[32:35], v[176:179], v[196:199], v[32:35]
	v_mfma_f32_16x16x32_bf16 v[20:23], v[168:171], v[204:207], v[20:23]
	v_mfma_f32_16x16x32_bf16 v[16:19], v[176:179], v[204:207], v[16:19]
	v_mfma_f32_16x16x32_bf16 v[4:7], v[168:171], v[212:215], v[4:7]
	v_mfma_f32_16x16x32_bf16 v[0:3], v[176:179], v[212:215], v[0:3]
	v_mfma_f32_16x16x32_bf16 v[52:55], v[172:175], v[192:195], v[52:55]
	v_mfma_f32_16x16x32_bf16 v[48:51], v[184:187], v[192:195], v[48:51]
	v_mfma_f32_16x16x32_bf16 v[36:39], v[172:175], v[200:203], v[36:39]
	v_mfma_f32_16x16x32_bf16 v[32:35], v[184:187], v[200:203], v[32:35]
	v_mfma_f32_16x16x32_bf16 v[20:23], v[172:175], v[208:211], v[20:23]
	v_mfma_f32_16x16x32_bf16 v[16:19], v[184:187], v[208:211], v[16:19]
	s_setprio 3
	s_barrier
	v_mfma_f32_16x16x32_bf16 v[4:7], v[172:175], v[216:219], v[4:7]
	v_mfma_f32_16x16x32_bf16 v[0:3], v[184:187], v[216:219], v[0:3]
	s_setprio 0
	s_add_i32 s50, 0, 0x18000
	v_add_u32_e32 v155, s50, v149
	s_add_i32 s51, 0, 0x1c000
	ds_read_b128 v[144:147], v155
	ds_read_b128 v[156:159], v155 offset:1024
	ds_read_b128 v[160:163], v155 offset:2048
	ds_read_b128 v[164:167], v155 offset:3072
	v_add_u32_e32 v155, s51, v149
	ds_read_b128 v[168:171], v155
	ds_read_b128 v[172:175], v155 offset:1024
	ds_read_b128 v[176:179], v155 offset:2048
	ds_read_b128 v[184:187], v155 offset:3072
	v_lshl_add_u64 v[224:225], s[28:29], 0, v[128:129]
	s_mov_b32 m0, s34
	v_lshl_add_u64 v[226:227], s[28:29], 0, v[132:133]
	s_mov_b64 exec, s[98:99]
	global_load_lds_dwordx4 v[224:225], off
	s_mov_b32 m0, s35
	s_nop 0
	global_load_lds_dwordx4 v[226:227], off
	s_mov_b64 exec, -1
	s_add_u32 s28, s28, 0x40000
	s_addc_u32 s29, s29, 0
	s_mov_b32 m0, s36
	v_lshl_add_u64 v[228:229], s[28:29], 0, v[128:129]
	ds_read_b128 v[188:191], v153 offset:32768
	ds_read_b128 v[192:195], v153 offset:33792
	ds_read_b128 v[196:199], v153 offset:34816
	ds_read_b128 v[200:203], v153 offset:35840
	ds_read_b128 v[204:207], v153 offset:36864
	ds_read_b128 v[208:211], v153 offset:37888
	ds_read_b128 v[212:215], v153 offset:38912
	ds_read_b128 v[216:219], v153 offset:39936
	s_mov_b64 exec, s[98:99]
	global_load_lds_dwordx4 v[228:229], off
	v_lshl_add_u64 v[228:229], s[28:29], 0, v[132:133]
	s_mov_b32 m0, s37
	s_nop 0
	global_load_lds_dwordx4 v[228:229], off
	s_mov_b64 exec, -1
	s_cmp_lg_u32 s99, 0
	s_cbranch_scc1 .Lng_5_2
	s_waitcnt vmcnt(0)
.Lng_5_2:
	s_waitcnt vmcnt(8)
	s_waitcnt lgkmcnt(0)
	s_barrier
	s_waitcnt lgkmcnt(0)
	v_mfma_f32_16x16x32_bf16 v[124:127], v[144:147], v[188:191], v[124:127]
	v_mfma_f32_16x16x32_bf16 v[120:123], v[160:163], v[188:191], v[120:123]
	v_mfma_f32_16x16x32_bf16 v[108:111], v[144:147], v[196:199], v[108:111]
	v_mfma_f32_16x16x32_bf16 v[104:107], v[160:163], v[196:199], v[104:107]
	v_mfma_f32_16x16x32_bf16 v[92:95], v[144:147], v[204:207], v[92:95]
	v_mfma_f32_16x16x32_bf16 v[88:91], v[160:163], v[204:207], v[88:91]
	v_mfma_f32_16x16x32_bf16 v[76:79], v[144:147], v[212:215], v[76:79]
	v_mfma_f32_16x16x32_bf16 v[72:75], v[160:163], v[212:215], v[72:75]
	v_mfma_f32_16x16x32_bf16 v[124:127], v[156:159], v[192:195], v[124:127]
	v_mfma_f32_16x16x32_bf16 v[120:123], v[164:167], v[192:195], v[120:123]
	v_mfma_f32_16x16x32_bf16 v[108:111], v[156:159], v[200:203], v[108:111]
	v_mfma_f32_16x16x32_bf16 v[104:107], v[164:167], v[200:203], v[104:107]
	v_mfma_f32_16x16x32_bf16 v[92:95], v[156:159], v[208:211], v[92:95]
	v_mfma_f32_16x16x32_bf16 v[88:91], v[164:167], v[208:211], v[88:91]
	v_mfma_f32_16x16x32_bf16 v[76:79], v[156:159], v[216:219], v[76:79]
	v_mfma_f32_16x16x32_bf16 v[72:75], v[164:167], v[216:219], v[72:75]
	v_mfma_f32_16x16x32_bf16 v[116:119], v[168:171], v[188:191], v[116:119]
	v_mfma_f32_16x16x32_bf16 v[112:115], v[176:179], v[188:191], v[112:115]
	v_mfma_f32_16x16x32_bf16 v[100:103], v[168:171], v[196:199], v[100:103]
	v_mfma_f32_16x16x32_bf16 v[96:99], v[176:179], v[196:199], v[96:99]
	v_mfma_f32_16x16x32_bf16 v[84:87], v[168:171], v[204:207], v[84:87]
	v_mfma_f32_16x16x32_bf16 v[80:83], v[176:179], v[204:207], v[80:83]
	v_mfma_f32_16x16x32_bf16 v[68:71], v[168:171], v[212:215], v[68:71]
	v_mfma_f32_16x16x32_bf16 v[64:67], v[176:179], v[212:215], v[64:67]
	v_mfma_f32_16x16x32_bf16 v[116:119], v[172:175], v[192:195], v[116:119]
	v_mfma_f32_16x16x32_bf16 v[112:115], v[184:187], v[192:195], v[112:115]
	v_mfma_f32_16x16x32_bf16 v[100:103], v[172:175], v[200:203], v[100:103]
	v_mfma_f32_16x16x32_bf16 v[96:99], v[184:187], v[200:203], v[96:99]
	v_mfma_f32_16x16x32_bf16 v[84:87], v[172:175], v[208:211], v[84:87]
	v_mfma_f32_16x16x32_bf16 v[80:83], v[184:187], v[208:211], v[80:83]
	s_setprio 3
	s_barrier
	v_mfma_f32_16x16x32_bf16 v[68:71], v[172:175], v[216:219], v[68:71]
	v_mfma_f32_16x16x32_bf16 v[64:67], v[184:187], v[216:219], v[64:67]
	s_setprio 0
	s_add_i32 s28, s50, s33
	v_lshl_add_u64 v[220:221], v[220:221], 0, s[10:11]
	s_mov_b32 m0, s28
	ds_read_b128 v[188:191], v153 offset:49152
	ds_read_b128 v[192:195], v153 offset:50176
	ds_read_b128 v[196:199], v153 offset:51200
	ds_read_b128 v[200:203], v153 offset:52224
	ds_read_b128 v[204:207], v153 offset:53248
	ds_read_b128 v[208:211], v153 offset:54272
	ds_read_b128 v[212:215], v153 offset:55296
	ds_read_b128 v[216:219], v153 offset:56320
	s_mov_b64 exec, s[98:99]
	global_load_lds_dwordx4 v[220:221], off
	s_add_i32 m0, s28, 0x2000
	s_add_u32 s26, s26, 0x40080
	v_lshl_add_u64 v[220:221], v[222:223], 0, s[10:11]
	s_addc_u32 s27, s27, 0
	s_add_i32 s28, s51, s33
	global_load_lds_dwordx4 v[220:221], off
	v_lshl_add_u64 v[220:221], s[26:27], 0, v[130:131]
	s_mov_b32 m0, s28
	s_nop 0
	global_load_lds_dwordx4 v[220:221], off
	v_lshl_add_u64 v[220:221], s[26:27], 0, v[134:135]
	s_add_i32 m0, s28, 0x2000
	s_nop 0
	global_load_lds_dwordx4 v[220:221], off
	s_mov_b64 exec, -1
	s_cmp_lg_u32 s99, 0
	s_cbranch_scc1 .Lng_5_3
	s_waitcnt vmcnt(0)
.Lng_5_3:
	s_waitcnt vmcnt(6)
	s_waitcnt lgkmcnt(0)
	s_barrier
	s_waitcnt lgkmcnt(0)
	v_mfma_f32_16x16x32_bf16 v[60:63], v[144:147], v[188:191], v[60:63]
	v_mfma_f32_16x16x32_bf16 v[56:59], v[160:163], v[188:191], v[56:59]
	v_mfma_f32_16x16x32_bf16 v[44:47], v[144:147], v[196:199], v[44:47]
	v_mfma_f32_16x16x32_bf16 v[40:43], v[160:163], v[196:199], v[40:43]
	v_mfma_f32_16x16x32_bf16 v[28:31], v[144:147], v[204:207], v[28:31]
	v_mfma_f32_16x16x32_bf16 v[24:27], v[160:163], v[204:207], v[24:27]
	v_mfma_f32_16x16x32_bf16 v[12:15], v[144:147], v[212:215], v[12:15]
	v_mfma_f32_16x16x32_bf16 v[8:11], v[160:163], v[212:215], v[8:11]
	v_mfma_f32_16x16x32_bf16 v[60:63], v[156:159], v[192:195], v[60:63]
	v_mfma_f32_16x16x32_bf16 v[56:59], v[164:167], v[192:195], v[56:59]
	v_mfma_f32_16x16x32_bf16 v[44:47], v[156:159], v[200:203], v[44:47]
	v_mfma_f32_16x16x32_bf16 v[40:43], v[164:167], v[200:203], v[40:43]
	v_mfma_f32_16x16x32_bf16 v[28:31], v[156:159], v[208:211], v[28:31]
	v_mfma_f32_16x16x32_bf16 v[24:27], v[164:167], v[208:211], v[24:27]
	v_mfma_f32_16x16x32_bf16 v[12:15], v[156:159], v[216:219], v[12:15]
	v_mfma_f32_16x16x32_bf16 v[8:11], v[164:167], v[216:219], v[8:11]
	v_mfma_f32_16x16x32_bf16 v[52:55], v[168:171], v[188:191], v[52:55]
	v_mfma_f32_16x16x32_bf16 v[48:51], v[176:179], v[188:191], v[48:51]
	v_mfma_f32_16x16x32_bf16 v[36:39], v[168:171], v[196:199], v[36:39]
	v_mfma_f32_16x16x32_bf16 v[32:35], v[176:179], v[196:199], v[32:35]
	v_mfma_f32_16x16x32_bf16 v[20:23], v[168:171], v[204:207], v[20:23]
	v_mfma_f32_16x16x32_bf16 v[16:19], v[176:179], v[204:207], v[16:19]
	v_mfma_f32_16x16x32_bf16 v[4:7], v[168:171], v[212:215], v[4:7]
	v_mfma_f32_16x16x32_bf16 v[0:3], v[176:179], v[212:215], v[0:3]
	v_mfma_f32_16x16x32_bf16 v[52:55], v[172:175], v[192:195], v[52:55]
	v_mfma_f32_16x16x32_bf16 v[48:51], v[184:187], v[192:195], v[48:51]
	v_mfma_f32_16x16x32_bf16 v[36:39], v[172:175], v[200:203], v[36:39]
	v_mfma_f32_16x16x32_bf16 v[32:35], v[184:187], v[200:203], v[32:35]
	v_mfma_f32_16x16x32_bf16 v[20:23], v[172:175], v[208:211], v[20:23]
	v_mfma_f32_16x16x32_bf16 v[16:19], v[184:187], v[208:211], v[16:19]
	s_setprio 3
	s_barrier
	v_mfma_f32_16x16x32_bf16 v[4:7], v[172:175], v[216:219], v[4:7]
	v_mfma_f32_16x16x32_bf16 v[0:3], v[184:187], v[216:219], v[0:3]
	s_setprio 0
	v_lshl_add_u64 v[220:221], v[224:225], 0, s[10:11]
	s_mov_b32 m0, s39
	s_nop 0
	s_mov_b64 exec, s[98:99]
	global_load_lds_dwordx4 v[220:221], off
	v_lshl_add_u64 v[220:221], v[226:227], 0, s[10:11]
	s_mov_b32 m0, s40
	s_nop 0
	global_load_lds_dwordx4 v[220:221], off
	s_mov_b64 exec, -1
	s_add_i32 s47, s47, 2
	s_add_u32 s24, s24, 0x100
	s_addc_u32 s25, s25, 0
	s_add_u32 s45, s45, 0x100
	s_addc_u32 s46, s46, 0
	s_cmp_gt_u32 s47, 13
	s_cbranch_scc0 .LBB0_1291
	s_and_b64 vcc, exec, s[12:13]
	s_cbranch_vccz .LBB0_1294
	s_barrier

.LBB0_1379:
	ds_read_b128 v[154:157], v151
	ds_read_b128 v[158:161], v151 offset:1024
	ds_read_b128 v[162:165], v151 offset:2048
	ds_read_b128 v[166:169], v151 offset:3072
	ds_read_b128 v[170:173], v152
	ds_read_b128 v[174:177], v152 offset:1024
	ds_read_b128 v[184:187], v152 offset:2048
	ds_read_b128 v[188:191], v152 offset:3072
	s_add_u32 s22, s20, 0xfffc0080
	s_addc_u32 s23, s21, -1
	s_cmp_eq_u32 s46, 12
	s_cselect_b32 s25, s13, s23
	s_cselect_b32 s24, s42, s22
	s_cselect_b32 s23, s11, s45
	s_cselect_b32 s22, s43, s44
	s_cselect_b32 s99, 0, -1
	s_or_b32 s99, s99, s100
	s_mov_b32 s98, s99
	v_lshl_add_u64 v[178:179], s[20:21], 0, v[136:137]
	s_add_i32 m0, s19, 0xc000
	ds_read_b128 v[192:195], v153
	ds_read_b128 v[196:199], v153 offset:1024
	ds_read_b128 v[200:203], v153 offset:2048
	ds_read_b128 v[204:207], v153 offset:3072
	ds_read_b128 v[208:211], v153 offset:4096
	ds_read_b128 v[212:215], v153 offset:5120
	ds_read_b128 v[216:219], v153 offset:6144
	ds_read_b128 v[220:223], v153 offset:7168
	global_load_lds_dwordx4 v[178:179], off
	v_lshl_add_u64 v[178:179], s[20:21], 0, v[138:139]
	s_add_i32 m0, s19, 0xe000
	s_nop 0
	global_load_lds_dwordx4 v[178:179], off
	s_waitcnt vmcnt(8)
	s_waitcnt lgkmcnt(0)
	s_barrier
	s_waitcnt lgkmcnt(0)
	v_mfma_f32_16x16x32_bf16 v[124:127], v[154:157], v[192:195], v[124:127]
	v_mfma_f32_16x16x32_bf16 v[116:119], v[162:165], v[192:195], v[116:119]
	v_mfma_f32_16x16x32_bf16 v[108:111], v[154:157], v[200:203], v[108:111]
	v_mfma_f32_16x16x32_bf16 v[100:103], v[162:165], v[200:203], v[100:103]
	v_mfma_f32_16x16x32_bf16 v[92:95], v[154:157], v[208:211], v[92:95]
	v_mfma_f32_16x16x32_bf16 v[84:87], v[162:165], v[208:211], v[84:87]
	v_mfma_f32_16x16x32_bf16 v[76:79], v[154:157], v[216:219], v[76:79]
	v_mfma_f32_16x16x32_bf16 v[68:71], v[162:165], v[216:219], v[68:71]
	v_mfma_f32_16x16x32_bf16 v[124:127], v[158:161], v[196:199], v[124:127]
	v_mfma_f32_16x16x32_bf16 v[116:119], v[166:169], v[196:199], v[116:119]
	v_mfma_f32_16x16x32_bf16 v[108:111], v[158:161], v[204:207], v[108:111]
	v_mfma_f32_16x16x32_bf16 v[100:103], v[166:169], v[204:207], v[100:103]
	v_mfma_f32_16x16x32_bf16 v[92:95], v[158:161], v[212:215], v[92:95]
	v_mfma_f32_16x16x32_bf16 v[84:87], v[166:169], v[212:215], v[84:87]
	v_mfma_f32_16x16x32_bf16 v[76:79], v[158:161], v[220:223], v[76:79]
	v_mfma_f32_16x16x32_bf16 v[68:71], v[166:169], v[220:223], v[68:71]
	v_mfma_f32_16x16x32_bf16 v[120:123], v[170:173], v[192:195], v[120:123]
	v_mfma_f32_16x16x32_bf16 v[112:115], v[184:187], v[192:195], v[112:115]
	v_mfma_f32_16x16x32_bf16 v[104:107], v[170:173], v[200:203], v[104:107]
	v_mfma_f32_16x16x32_bf16 v[96:99], v[184:187], v[200:203], v[96:99]
	v_mfma_f32_16x16x32_bf16 v[88:91], v[170:173], v[208:211], v[88:91]
	v_mfma_f32_16x16x32_bf16 v[80:83], v[184:187], v[208:211], v[80:83]
	v_mfma_f32_16x16x32_bf16 v[72:75], v[170:173], v[216:219], v[72:75]
	v_mfma_f32_16x16x32_bf16 v[64:67], v[184:187], v[216:219], v[64:67]
	v_mfma_f32_16x16x32_bf16 v[120:123], v[174:177], v[196:199], v[120:123]
	v_mfma_f32_16x16x32_bf16 v[112:115], v[188:191], v[196:199], v[112:115]
	v_mfma_f32_16x16x32_bf16 v[104:107], v[174:177], v[204:207], v[104:107]
	v_mfma_f32_16x16x32_bf16 v[96:99], v[188:191], v[204:207], v[96:99]
	v_mfma_f32_16x16x32_bf16 v[88:91], v[174:177], v[212:215], v[88:91]
	v_mfma_f32_16x16x32_bf16 v[80:83], v[188:191], v[212:215], v[80:83]
	s_setprio 3
	s_barrier
	v_mfma_f32_16x16x32_bf16 v[72:75], v[174:177], v[220:223], v[72:75]
	v_mfma_f32_16x16x32_bf16 v[64:67], v[188:191], v[220:223], v[64:67]
	s_setprio 0
	s_add_i32 s47, s36, s28
	v_lshl_add_u64 v[178:179], s[22:23], 0, v[132:133]
	s_mov_b32 m0, s47
	ds_read_b128 v[192:195], v153 offset:16384
	ds_read_b128 v[196:199], v153 offset:17408
	ds_read_b128 v[200:203], v153 offset:18432
	ds_read_b128 v[204:207], v153 offset:19456
	ds_read_b128 v[208:211], v153 offset:20480
	ds_read_b128 v[212:215], v153 offset:21504
	ds_read_b128 v[216:219], v153 offset:22528
	ds_read_b128 v[220:223], v153 offset:23552
	s_mov_b64 exec, s[98:99]
	global_load_lds_dwordx4 v[178:179], off
	s_add_i32 m0, s47, 0x2000
	s_add_u32 s48, s22, 0x40000
	v_lshl_add_u64 v[224:225], s[22:23], 0, v[128:129]
	s_addc_u32 s49, s23, 0
	s_add_i32 s47, s37, s28
	global_load_lds_dwordx4 v[224:225], off
	v_lshl_add_u64 v[226:227], s[48:49], 0, v[132:133]
	s_mov_b32 m0, s47
	global_load_lds_dwordx4 v[226:227], off
	v_lshl_add_u64 v[226:227], s[48:49], 0, v[128:129]
	s_add_i32 m0, s47, 0x2000
	s_nop 0
	global_load_lds_dwordx4 v[226:227], off
	s_mov_b64 exec, -1
	s_cmp_lg_u32 s99, 0
	s_cbranch_scc1 .Lng_6_1
	s_waitcnt vmcnt(0)
.Lng_6_1:
	s_waitcnt vmcnt(6)
	s_waitcnt lgkmcnt(0)
	s_barrier
	s_waitcnt lgkmcnt(0)
	v_mfma_f32_16x16x32_bf16 v[60:63], v[154:157], v[192:195], v[60:63]
	v_mfma_f32_16x16x32_bf16 v[52:55], v[162:165], v[192:195], v[52:55]
	v_mfma_f32_16x16x32_bf16 v[44:47], v[154:157], v[200:203], v[44:47]
	v_mfma_f32_16x16x32_bf16 v[36:39], v[162:165], v[200:203], v[36:39]
	v_mfma_f32_16x16x32_bf16 v[28:31], v[154:157], v[208:211], v[28:31]
	v_mfma_f32_16x16x32_bf16 v[20:23], v[162:165], v[208:211], v[20:23]
	v_mfma_f32_16x16x32_bf16 v[12:15], v[154:157], v[216:219], v[12:15]
	v_mfma_f32_16x16x32_bf16 v[4:7], v[162:165], v[216:219], v[4:7]
	v_mfma_f32_16x16x32_bf16 v[60:63], v[158:161], v[196:199], v[60:63]
	v_mfma_f32_16x16x32_bf16 v[52:55], v[166:169], v[196:199], v[52:55]
	v_mfma_f32_16x16x32_bf16 v[44:47], v[158:161], v[204:207], v[44:47]
	v_mfma_f32_16x16x32_bf16 v[36:39], v[166:169], v[204:207], v[36:39]
	v_mfma_f32_16x16x32_bf16 v[28:31], v[158:161], v[212:215], v[28:31]
	v_mfma_f32_16x16x32_bf16 v[20:23], v[166:169], v[212:215], v[20:23]
	v_mfma_f32_16x16x32_bf16 v[12:15], v[158:161], v[220:223], v[12:15]
	v_mfma_f32_16x16x32_bf16 v[4:7], v[166:169], v[220:223], v[4:7]
	v_mfma_f32_16x16x32_bf16 v[56:59], v[170:173], v[192:195], v[56:59]
	v_mfma_f32_16x16x32_bf16 v[48:51], v[184:187], v[192:195], v[48:51]
	v_mfma_f32_16x16x32_bf16 v[40:43], v[170:173], v[200:203], v[40:43]
	v_mfma_f32_16x16x32_bf16 v[32:35], v[184:187], v[200:203], v[32:35]
	v_mfma_f32_16x16x32_bf16 v[24:27], v[170:173], v[208:211], v[24:27]
	v_mfma_f32_16x16x32_bf16 v[16:19], v[184:187], v[208:211], v[16:19]
	v_mfma_f32_16x16x32_bf16 v[8:11], v[170:173], v[216:219], v[8:11]
	v_mfma_f32_16x16x32_bf16 v[0:3], v[184:187], v[216:219], v[0:3]
	v_mfma_f32_16x16x32_bf16 v[56:59], v[174:177], v[196:199], v[56:59]
	v_mfma_f32_16x16x32_bf16 v[48:51], v[188:191], v[196:199], v[48:51]
	v_mfma_f32_16x16x32_bf16 v[40:43], v[174:177], v[204:207], v[40:43]
	v_mfma_f32_16x16x32_bf16 v[32:35], v[188:191], v[204:207], v[32:35]
	v_mfma_f32_16x16x32_bf16 v[24:27], v[174:177], v[212:215], v[24:27]
	v_mfma_f32_16x16x32_bf16 v[16:19], v[188:191], v[212:215], v[16:19]
	s_setprio 3
	s_barrier
	v_mfma_f32_16x16x32_bf16 v[8:11], v[174:177], v[220:223], v[8:11]
	v_mfma_f32_16x16x32_bf16 v[0:3], v[188:191], v[220:223], v[0:3]
	s_setprio 0
	s_add_i32 s47, 0, 0x18000
	s_add_i32 s48, 0, 0x1c000
	v_add_u32_e32 v166, s47, v145
	v_add_u32_e32 v180, s48, v145
	ds_read_b128 v[154:157], v166
	ds_read_b128 v[158:161], v166 offset:1024
	ds_read_b128 v[162:165], v166 offset:2048
	ds_read_b128 v[166:169], v166 offset:3072
	ds_read_b128 v[170:173], v180
	ds_read_b128 v[174:177], v180 offset:1024
	ds_read_b128 v[184:187], v180 offset:2048
	ds_read_b128 v[188:191], v180 offset:3072
	v_lshl_add_u64 v[226:227], s[24:25], 0, v[134:135]
	s_mov_b32 m0, s19
	v_lshl_add_u64 v[228:229], s[24:25], 0, v[130:131]
	s_mov_b64 exec, s[98:99]
	global_load_lds_dwordx4 v[226:227], off
	s_mov_b32 m0, s30
	s_nop 0
	global_load_lds_dwordx4 v[228:229], off
	s_mov_b64 exec, -1
	s_add_u32 s24, s24, 0x40000
	s_addc_u32 s25, s25, 0
	s_mov_b32 m0, s31
	v_lshl_add_u64 v[230:231], s[24:25], 0, v[134:135]
	ds_read_b128 v[192:195], v153 offset:32768
	ds_read_b128 v[196:199], v153 offset:33792
	ds_read_b128 v[200:203], v153 offset:34816
	ds_read_b128 v[204:207], v153 offset:35840
	ds_read_b128 v[208:211], v153 offset:36864
	ds_read_b128 v[212:215], v153 offset:37888
	ds_read_b128 v[216:219], v153 offset:38912
	ds_read_b128 v[220:223], v153 offset:39936
	s_mov_b64 exec, s[98:99]
	global_load_lds_dwordx4 v[230:231], off
	v_lshl_add_u64 v[230:231], s[24:25], 0, v[130:131]
	s_mov_b32 m0, s33
	s_nop 0
	global_load_lds_dwordx4 v[230:231], off
	s_mov_b64 exec, -1
	s_cmp_lg_u32 s99, 0
	s_cbranch_scc1 .Lng_6_2
	s_waitcnt vmcnt(0)
.Lng_6_2:
	s_waitcnt vmcnt(8)
	s_waitcnt lgkmcnt(0)
	s_barrier
	s_waitcnt lgkmcnt(0)
	v_mfma_f32_16x16x32_bf16 v[124:127], v[154:157], v[192:195], v[124:127]
	v_mfma_f32_16x16x32_bf16 v[116:119], v[162:165], v[192:195], v[116:119]
	v_mfma_f32_16x16x32_bf16 v[108:111], v[154:157], v[200:203], v[108:111]
	v_mfma_f32_16x16x32_bf16 v[100:103], v[162:165], v[200:203], v[100:103]
	v_mfma_f32_16x16x32_bf16 v[92:95], v[154:157], v[208:211], v[92:95]
	v_mfma_f32_16x16x32_bf16 v[84:87], v[162:165], v[208:211], v[84:87]
	v_mfma_f32_16x16x32_bf16 v[76:79], v[154:157], v[216:219], v[76:79]
	v_mfma_f32_16x16x32_bf16 v[68:71], v[162:165], v[216:219], v[68:71]
	v_mfma_f32_16x16x32_bf16 v[124:127], v[158:161], v[196:199], v[124:127]
	v_mfma_f32_16x16x32_bf16 v[116:119], v[166:169], v[196:199], v[116:119]
	v_mfma_f32_16x16x32_bf16 v[108:111], v[158:161], v[204:207], v[108:111]
	v_mfma_f32_16x16x32_bf16 v[100:103], v[166:169], v[204:207], v[100:103]
	v_mfma_f32_16x16x32_bf16 v[92:95], v[158:161], v[212:215], v[92:95]
	v_mfma_f32_16x16x32_bf16 v[84:87], v[166:169], v[212:215], v[84:87]
	v_mfma_f32_16x16x32_bf16 v[76:79], v[158:161], v[220:223], v[76:79]
	v_mfma_f32_16x16x32_bf16 v[68:71], v[166:169], v[220:223], v[68:71]
	v_mfma_f32_16x16x32_bf16 v[120:123], v[170:173], v[192:195], v[120:123]
	v_mfma_f32_16x16x32_bf16 v[112:115], v[184:187], v[192:195], v[112:115]
	v_mfma_f32_16x16x32_bf16 v[104:107], v[170:173], v[200:203], v[104:107]
	v_mfma_f32_16x16x32_bf16 v[96:99], v[184:187], v[200:203], v[96:99]
	v_mfma_f32_16x16x32_bf16 v[88:91], v[170:173], v[208:211], v[88:91]
	v_mfma_f32_16x16x32_bf16 v[80:83], v[184:187], v[208:211], v[80:83]
	v_mfma_f32_16x16x32_bf16 v[72:75], v[170:173], v[216:219], v[72:75]
	v_mfma_f32_16x16x32_bf16 v[64:67], v[184:187], v[216:219], v[64:67]
	v_mfma_f32_16x16x32_bf16 v[120:123], v[174:177], v[196:199], v[120:123]
	v_mfma_f32_16x16x32_bf16 v[112:115], v[188:191], v[196:199], v[112:115]
	v_mfma_f32_16x16x32_bf16 v[104:107], v[174:177], v[204:207], v[104:107]
	v_mfma_f32_16x16x32_bf16 v[96:99], v[188:191], v[204:207], v[96:99]
	v_mfma_f32_16x16x32_bf16 v[88:91], v[174:177], v[212:215], v[88:91]
	v_mfma_f32_16x16x32_bf16 v[80:83], v[188:191], v[212:215], v[80:83]
	s_setprio 3
	s_barrier
	v_mfma_f32_16x16x32_bf16 v[72:75], v[174:177], v[220:223], v[72:75]
	v_mfma_f32_16x16x32_bf16 v[64:67], v[188:191], v[220:223], v[64:67]
	s_setprio 0
	s_add_i32 s24, s47, s28
	v_lshl_add_u64 v[178:179], v[178:179], 0, s[6:7]
	s_mov_b32 m0, s24
	ds_read_b128 v[192:195], v153 offset:49152
	ds_read_b128 v[196:199], v153 offset:50176
	ds_read_b128 v[200:203], v153 offset:51200
	ds_read_b128 v[204:207], v153 offset:52224
	ds_read_b128 v[208:211], v153 offset:53248
	ds_read_b128 v[212:215], v153 offset:54272
	ds_read_b128 v[216:219], v153 offset:55296
	ds_read_b128 v[220:223], v153 offset:56320
	s_mov_b64 exec, s[98:99]
	global_load_lds_dwordx4 v[178:179], off
	s_add_i32 m0, s24, 0x2000
	s_add_u32 s22, s22, 0x40080
	v_lshl_add_u64 v[178:179], v[224:225], 0, s[6:7]
	s_addc_u32 s23, s23, 0
	s_add_i32 s24, s48, s28
	global_load_lds_dwordx4 v[178:179], off
	v_lshl_add_u64 v[178:179], s[22:23], 0, v[132:133]
	s_mov_b32 m0, s24
	s_nop 0
	global_load_lds_dwordx4 v[178:179], off
	v_lshl_add_u64 v[178:179], s[22:23], 0, v[128:129]
	s_add_i32 m0, s24, 0x2000
	s_nop 0
	global_load_lds_dwordx4 v[178:179], off
	s_mov_b64 exec, -1
	s_cmp_lg_u32 s99, 0
	s_cbranch_scc1 .Lng_6_3
	s_waitcnt vmcnt(0)
.Lng_6_3:
	s_waitcnt vmcnt(6)
	s_waitcnt lgkmcnt(0)
	s_barrier
	s_waitcnt lgkmcnt(0)
	v_mfma_f32_16x16x32_bf16 v[60:63], v[154:157], v[192:195], v[60:63]
	v_mfma_f32_16x16x32_bf16 v[52:55], v[162:165], v[192:195], v[52:55]
	v_mfma_f32_16x16x32_bf16 v[44:47], v[154:157], v[200:203], v[44:47]
	v_mfma_f32_16x16x32_bf16 v[36:39], v[162:165], v[200:203], v[36:39]
	v_mfma_f32_16x16x32_bf16 v[28:31], v[154:157], v[208:211], v[28:31]
	v_mfma_f32_16x16x32_bf16 v[20:23], v[162:165], v[208:211], v[20:23]
	v_mfma_f32_16x16x32_bf16 v[12:15], v[154:157], v[216:219], v[12:15]
	v_mfma_f32_16x16x32_bf16 v[4:7], v[162:165], v[216:219], v[4:7]
	v_mfma_f32_16x16x32_bf16 v[60:63], v[158:161], v[196:199], v[60:63]
	v_mfma_f32_16x16x32_bf16 v[52:55], v[166:169], v[196:199], v[52:55]
	v_mfma_f32_16x16x32_bf16 v[44:47], v[158:161], v[204:207], v[44:47]
	v_mfma_f32_16x16x32_bf16 v[36:39], v[166:169], v[204:207], v[36:39]
	v_mfma_f32_16x16x32_bf16 v[28:31], v[158:161], v[212:215], v[28:31]
	v_mfma_f32_16x16x32_bf16 v[20:23], v[166:169], v[212:215], v[20:23]
	v_mfma_f32_16x16x32_bf16 v[12:15], v[158:161], v[220:223], v[12:15]
	v_mfma_f32_16x16x32_bf16 v[4:7], v[166:169], v[220:223], v[4:7]
	v_mfma_f32_16x16x32_bf16 v[56:59], v[170:173], v[192:195], v[56:59]
	v_mfma_f32_16x16x32_bf16 v[48:51], v[184:187], v[192:195], v[48:51]
	v_mfma_f32_16x16x32_bf16 v[40:43], v[170:173], v[200:203], v[40:43]
	v_mfma_f32_16x16x32_bf16 v[32:35], v[184:187], v[200:203], v[32:35]
	v_mfma_f32_16x16x32_bf16 v[24:27], v[170:173], v[208:211], v[24:27]
	v_mfma_f32_16x16x32_bf16 v[16:19], v[184:187], v[208:211], v[16:19]
	v_mfma_f32_16x16x32_bf16 v[8:11], v[170:173], v[216:219], v[8:11]
	v_mfma_f32_16x16x32_bf16 v[0:3], v[184:187], v[216:219], v[0:3]
	v_mfma_f32_16x16x32_bf16 v[56:59], v[174:177], v[196:199], v[56:59]
	v_mfma_f32_16x16x32_bf16 v[48:51], v[188:191], v[196:199], v[48:51]
	v_mfma_f32_16x16x32_bf16 v[40:43], v[174:177], v[204:207], v[40:43]
	v_mfma_f32_16x16x32_bf16 v[32:35], v[188:191], v[204:207], v[32:35]
	v_mfma_f32_16x16x32_bf16 v[24:27], v[174:177], v[212:215], v[24:27]
	v_mfma_f32_16x16x32_bf16 v[16:19], v[188:191], v[212:215], v[16:19]
	s_setprio 3
	s_barrier
	v_mfma_f32_16x16x32_bf16 v[8:11], v[174:177], v[220:223], v[8:11]
	v_mfma_f32_16x16x32_bf16 v[0:3], v[188:191], v[220:223], v[0:3]
	s_setprio 0
	v_lshl_add_u64 v[178:179], v[226:227], 0, s[6:7]
	s_mov_b32 m0, s34
	s_nop 0
	s_mov_b64 exec, s[98:99]
	global_load_lds_dwordx4 v[178:179], off
	v_lshl_add_u64 v[178:179], v[228:229], 0, s[6:7]
	s_mov_b32 m0, s35
	s_nop 0
	global_load_lds_dwordx4 v[178:179], off
	s_mov_b64 exec, -1
	s_add_i32 s46, s46, 2
	s_add_u32 s20, s20, 0x100
	s_addc_u32 s21, s21, 0
	s_add_u32 s44, s44, 0x100
	s_addc_u32 s45, s45, 0
	s_cmp_gt_u32 s46, 13
	s_cbranch_scc0 .LBB0_1379
	s_and_b64 vcc, exec, s[8:9]
	s_cbranch_vccz .LBB0_1382
	s_barrier

.LBB0_1461:
	ds_read_b128 v[144:147], v151
	ds_read_b128 v[156:159], v151 offset:1024
	ds_read_b128 v[160:163], v151 offset:2048
	ds_read_b128 v[164:167], v151 offset:3072
	ds_read_b128 v[168:171], v152
	ds_read_b128 v[172:175], v152 offset:1024
	ds_read_b128 v[176:179], v152 offset:2048
	ds_read_b128 v[182:185], v152 offset:3072
	s_add_u32 s20, s18, 0x100
	s_addc_u32 s21, s19, 0
	s_cmp_eq_u32 s45, 40
	s_cselect_b32 s25, s7, s21
	s_cselect_b32 s24, s6, s20
	s_cselect_b32 s23, s17, s44
	s_cselect_b32 s22, s16, s43
	s_cselect_b32 s99, 0, -1
	s_or_b32 s99, s99, s100
	s_mov_b32 s98, s99
	v_lshl_add_u64 v[218:219], s[18:19], 0, v[136:137]
	s_add_i32 m0, s29, 0xc000
	ds_read_b128 v[186:189], v153
	ds_read_b128 v[190:193], v153 offset:1024
	ds_read_b128 v[194:197], v153 offset:2048
	ds_read_b128 v[198:201], v153 offset:3072
	ds_read_b128 v[202:205], v153 offset:4096
	ds_read_b128 v[206:209], v153 offset:5120
	ds_read_b128 v[210:213], v153 offset:6144
	ds_read_b128 v[214:217], v153 offset:7168
	global_load_lds_dwordx4 v[218:219], off
	v_lshl_add_u64 v[218:219], s[18:19], 0, v[138:139]
	s_add_i32 m0, s29, 0xe000
	s_nop 0
	global_load_lds_dwordx4 v[218:219], off
	s_waitcnt vmcnt(8)
	s_waitcnt lgkmcnt(0)
	s_barrier
	s_waitcnt lgkmcnt(0)
	v_mfma_f32_16x16x32_bf16 v[124:127], v[144:147], v[186:189], v[124:127]
	v_mfma_f32_16x16x32_bf16 v[120:123], v[160:163], v[186:189], v[120:123]
	v_mfma_f32_16x16x32_bf16 v[108:111], v[144:147], v[194:197], v[108:111]
	v_mfma_f32_16x16x32_bf16 v[104:107], v[160:163], v[194:197], v[104:107]
	v_mfma_f32_16x16x32_bf16 v[92:95], v[144:147], v[202:205], v[92:95]
	v_mfma_f32_16x16x32_bf16 v[88:91], v[160:163], v[202:205], v[88:91]
	v_mfma_f32_16x16x32_bf16 v[76:79], v[144:147], v[210:213], v[76:79]
	v_mfma_f32_16x16x32_bf16 v[72:75], v[160:163], v[210:213], v[72:75]
	v_mfma_f32_16x16x32_bf16 v[124:127], v[156:159], v[190:193], v[124:127]
	v_mfma_f32_16x16x32_bf16 v[120:123], v[164:167], v[190:193], v[120:123]
	v_mfma_f32_16x16x32_bf16 v[108:111], v[156:159], v[198:201], v[108:111]
	v_mfma_f32_16x16x32_bf16 v[104:107], v[164:167], v[198:201], v[104:107]
	v_mfma_f32_16x16x32_bf16 v[92:95], v[156:159], v[206:209], v[92:95]
	v_mfma_f32_16x16x32_bf16 v[88:91], v[164:167], v[206:209], v[88:91]
	v_mfma_f32_16x16x32_bf16 v[76:79], v[156:159], v[214:217], v[76:79]
	v_mfma_f32_16x16x32_bf16 v[72:75], v[164:167], v[214:217], v[72:75]
	v_mfma_f32_16x16x32_bf16 v[116:119], v[168:171], v[186:189], v[116:119]
	v_mfma_f32_16x16x32_bf16 v[112:115], v[176:179], v[186:189], v[112:115]
	v_mfma_f32_16x16x32_bf16 v[100:103], v[168:171], v[194:197], v[100:103]
	v_mfma_f32_16x16x32_bf16 v[96:99], v[176:179], v[194:197], v[96:99]
	v_mfma_f32_16x16x32_bf16 v[84:87], v[168:171], v[202:205], v[84:87]
	v_mfma_f32_16x16x32_bf16 v[80:83], v[176:179], v[202:205], v[80:83]
	v_mfma_f32_16x16x32_bf16 v[68:71], v[168:171], v[210:213], v[68:71]
	v_mfma_f32_16x16x32_bf16 v[64:67], v[176:179], v[210:213], v[64:67]
	v_mfma_f32_16x16x32_bf16 v[116:119], v[172:175], v[190:193], v[116:119]
	v_mfma_f32_16x16x32_bf16 v[112:115], v[182:185], v[190:193], v[112:115]
	v_mfma_f32_16x16x32_bf16 v[100:103], v[172:175], v[198:201], v[100:103]
	v_mfma_f32_16x16x32_bf16 v[96:99], v[182:185], v[198:201], v[96:99]
	v_mfma_f32_16x16x32_bf16 v[84:87], v[172:175], v[206:209], v[84:87]
	v_mfma_f32_16x16x32_bf16 v[80:83], v[182:185], v[206:209], v[80:83]
	s_setprio 3
	s_barrier
	v_mfma_f32_16x16x32_bf16 v[68:71], v[172:175], v[214:217], v[68:71]
	v_mfma_f32_16x16x32_bf16 v[64:67], v[182:185], v[214:217], v[64:67]
	s_setprio 0
	s_add_i32 s18, s37, s28
	v_lshl_add_u64 v[218:219], s[22:23], 0, v[130:131]
	s_mov_b32 m0, s18
	ds_read_b128 v[186:189], v153 offset:16384
	ds_read_b128 v[190:193], v153 offset:17408
	ds_read_b128 v[194:197], v153 offset:18432
	ds_read_b128 v[198:201], v153 offset:19456
	ds_read_b128 v[202:205], v153 offset:20480
	ds_read_b128 v[206:209], v153 offset:21504
	ds_read_b128 v[210:213], v153 offset:22528
	ds_read_b128 v[214:217], v153 offset:23552
	s_mov_b64 exec, s[98:99]
	global_load_lds_dwordx4 v[218:219], off
	s_add_i32 m0, s18, 0x2000
	s_add_u32 s18, s22, 0xb0000
	v_lshl_add_u64 v[220:221], s[22:23], 0, v[134:135]
	s_addc_u32 s19, s23, 0
	s_add_i32 s46, s38, s28
	global_load_lds_dwordx4 v[220:221], off
	v_lshl_add_u64 v[222:223], s[18:19], 0, v[130:131]
	s_mov_b32 m0, s46
	global_load_lds_dwordx4 v[222:223], off
	v_lshl_add_u64 v[222:223], s[18:19], 0, v[134:135]
	s_add_i32 m0, s46, 0x2000
	s_nop 0
	global_load_lds_dwordx4 v[222:223], off
	s_mov_b64 exec, -1
	s_cmp_lg_u32 s99, 0
	s_cbranch_scc1 .Lng_7_1
	s_waitcnt vmcnt(0)
.Lng_7_1:
	s_waitcnt vmcnt(6)
	s_waitcnt lgkmcnt(0)
	s_barrier
	s_waitcnt lgkmcnt(0)
	v_mfma_f32_16x16x32_bf16 v[60:63], v[144:147], v[186:189], v[60:63]
	v_mfma_f32_16x16x32_bf16 v[56:59], v[160:163], v[186:189], v[56:59]
	v_mfma_f32_16x16x32_bf16 v[44:47], v[144:147], v[194:197], v[44:47]
	v_mfma_f32_16x16x32_bf16 v[40:43], v[160:163], v[194:197], v[40:43]
	v_mfma_f32_16x16x32_bf16 v[28:31], v[144:147], v[202:205], v[28:31]
	v_mfma_f32_16x16x32_bf16 v[24:27], v[160:163], v[202:205], v[24:27]
	v_mfma_f32_16x16x32_bf16 v[12:15], v[144:147], v[210:213], v[12:15]
	v_mfma_f32_16x16x32_bf16 v[8:11], v[160:163], v[210:213], v[8:11]
	v_mfma_f32_16x16x32_bf16 v[60:63], v[156:159], v[190:193], v[60:63]
	v_mfma_f32_16x16x32_bf16 v[56:59], v[164:167], v[190:193], v[56:59]
	v_mfma_f32_16x16x32_bf16 v[44:47], v[156:159], v[198:201], v[44:47]
	v_mfma_f32_16x16x32_bf16 v[40:43], v[164:167], v[198:201], v[40:43]
	v_mfma_f32_16x16x32_bf16 v[28:31], v[156:159], v[206:209], v[28:31]
	v_mfma_f32_16x16x32_bf16 v[24:27], v[164:167], v[206:209], v[24:27]
	v_mfma_f32_16x16x32_bf16 v[12:15], v[156:159], v[214:217], v[12:15]
	v_mfma_f32_16x16x32_bf16 v[8:11], v[164:167], v[214:217], v[8:11]
	v_mfma_f32_16x16x32_bf16 v[52:55], v[168:171], v[186:189], v[52:55]
	v_mfma_f32_16x16x32_bf16 v[48:51], v[176:179], v[186:189], v[48:51]
	v_mfma_f32_16x16x32_bf16 v[36:39], v[168:171], v[194:197], v[36:39]
	v_mfma_f32_16x16x32_bf16 v[32:35], v[176:179], v[194:197], v[32:35]
	v_mfma_f32_16x16x32_bf16 v[20:23], v[168:171], v[202:205], v[20:23]
	v_mfma_f32_16x16x32_bf16 v[16:19], v[176:179], v[202:205], v[16:19]
	v_mfma_f32_16x16x32_bf16 v[4:7], v[168:171], v[210:213], v[4:7]
	v_mfma_f32_16x16x32_bf16 v[0:3], v[176:179], v[210:213], v[0:3]
	v_mfma_f32_16x16x32_bf16 v[52:55], v[172:175], v[190:193], v[52:55]
	v_mfma_f32_16x16x32_bf16 v[48:51], v[182:185], v[190:193], v[48:51]
	v_mfma_f32_16x16x32_bf16 v[36:39], v[172:175], v[198:201], v[36:39]
	v_mfma_f32_16x16x32_bf16 v[32:35], v[182:185], v[198:201], v[32:35]
	v_mfma_f32_16x16x32_bf16 v[20:23], v[172:175], v[206:209], v[20:23]
	v_mfma_f32_16x16x32_bf16 v[16:19], v[182:185], v[206:209], v[16:19]
	s_setprio 3
	s_barrier
	v_mfma_f32_16x16x32_bf16 v[4:7], v[172:175], v[214:217], v[4:7]
	v_mfma_f32_16x16x32_bf16 v[0:3], v[182:185], v[214:217], v[0:3]
	s_setprio 0
	s_add_i32 s46, 0, 0x18000
	v_add_u32_e32 v155, s46, v149
	s_add_i32 s47, 0, 0x1c000
	ds_read_b128 v[144:147], v155
	ds_read_b128 v[156:159], v155 offset:1024
	ds_read_b128 v[160:163], v155 offset:2048
	ds_read_b128 v[164:167], v155 offset:3072
	v_add_u32_e32 v155, s47, v149
	ds_read_b128 v[168:171], v155
	ds_read_b128 v[172:175], v155 offset:1024
	ds_read_b128 v[176:179], v155 offset:2048
	ds_read_b128 v[182:185], v155 offset:3072
	s_add_u32 s18, s24, 0xb0000
	s_addc_u32 s19, s25, 0
	v_lshl_add_u64 v[222:223], s[24:25], 0, v[128:129]
	s_mov_b32 m0, s29
	v_lshl_add_u64 v[224:225], s[24:25], 0, v[132:133]
	s_mov_b64 exec, s[98:99]
	global_load_lds_dwordx4 v[222:223], off
	s_mov_b32 m0, s30
	s_nop 0
	global_load_lds_dwordx4 v[224:225], off
	s_mov_b64 exec, -1
	s_mov_b32 m0, s31
	v_lshl_add_u64 v[226:227], s[18:19], 0, v[128:129]
	ds_read_b128 v[186:189], v153 offset:32768
	ds_read_b128 v[190:193], v153 offset:33792
	ds_read_b128 v[194:197], v153 offset:34816
	ds_read_b128 v[198:201], v153 offset:35840
	ds_read_b128 v[202:205], v153 offset:36864
	ds_read_b128 v[206:209], v153 offset:37888
	ds_read_b128 v[210:213], v153 offset:38912
	ds_read_b128 v[214:217], v153 offset:39936
	s_mov_b64 exec, s[98:99]
	global_load_lds_dwordx4 v[226:227], off
	v_lshl_add_u64 v[226:227], s[18:19], 0, v[132:133]
	s_mov_b32 m0, s33
	s_nop 0
	global_load_lds_dwordx4 v[226:227], off
	s_mov_b64 exec, -1
	s_cmp_lg_u32 s99, 0
	s_cbranch_scc1 .Lng_7_2
	s_waitcnt vmcnt(0)
.Lng_7_2:
	s_waitcnt vmcnt(8)
	s_waitcnt lgkmcnt(0)
	s_barrier
	s_waitcnt lgkmcnt(0)
	v_mfma_f32_16x16x32_bf16 v[124:127], v[144:147], v[186:189], v[124:127]
	v_mfma_f32_16x16x32_bf16 v[120:123], v[160:163], v[186:189], v[120:123]
	v_mfma_f32_16x16x32_bf16 v[108:111], v[144:147], v[194:197], v[108:111]
	v_mfma_f32_16x16x32_bf16 v[104:107], v[160:163], v[194:197], v[104:107]
	v_mfma_f32_16x16x32_bf16 v[92:95], v[144:147], v[202:205], v[92:95]
	v_mfma_f32_16x16x32_bf16 v[88:91], v[160:163], v[202:205], v[88:91]
	v_mfma_f32_16x16x32_bf16 v[76:79], v[144:147], v[210:213], v[76:79]
	v_mfma_f32_16x16x32_bf16 v[72:75], v[160:163], v[210:213], v[72:75]
	v_mfma_f32_16x16x32_bf16 v[124:127], v[156:159], v[190:193], v[124:127]
	v_mfma_f32_16x16x32_bf16 v[120:123], v[164:167], v[190:193], v[120:123]
	v_mfma_f32_16x16x32_bf16 v[108:111], v[156:159], v[198:201], v[108:111]
	v_mfma_f32_16x16x32_bf16 v[104:107], v[164:167], v[198:201], v[104:107]
	v_mfma_f32_16x16x32_bf16 v[92:95], v[156:159], v[206:209], v[92:95]
	v_mfma_f32_16x16x32_bf16 v[88:91], v[164:167], v[206:209], v[88:91]
	v_mfma_f32_16x16x32_bf16 v[76:79], v[156:159], v[214:217], v[76:79]
	v_mfma_f32_16x16x32_bf16 v[72:75], v[164:167], v[214:217], v[72:75]
	v_mfma_f32_16x16x32_bf16 v[116:119], v[168:171], v[186:189], v[116:119]
	v_mfma_f32_16x16x32_bf16 v[112:115], v[176:179], v[186:189], v[112:115]
	v_mfma_f32_16x16x32_bf16 v[100:103], v[168:171], v[194:197], v[100:103]
	v_mfma_f32_16x16x32_bf16 v[96:99], v[176:179], v[194:197], v[96:99]
	v_mfma_f32_16x16x32_bf16 v[84:87], v[168:171], v[202:205], v[84:87]
	v_mfma_f32_16x16x32_bf16 v[80:83], v[176:179], v[202:205], v[80:83]
	v_mfma_f32_16x16x32_bf16 v[68:71], v[168:171], v[210:213], v[68:71]
	v_mfma_f32_16x16x32_bf16 v[64:67], v[176:179], v[210:213], v[64:67]
	v_mfma_f32_16x16x32_bf16 v[116:119], v[172:175], v[190:193], v[116:119]
	v_mfma_f32_16x16x32_bf16 v[112:115], v[182:185], v[190:193], v[112:115]
	v_mfma_f32_16x16x32_bf16 v[100:103], v[172:175], v[198:201], v[100:103]
	v_mfma_f32_16x16x32_bf16 v[96:99], v[182:185], v[198:201], v[96:99]
	v_mfma_f32_16x16x32_bf16 v[84:87], v[172:175], v[206:209], v[84:87]
	v_mfma_f32_16x16x32_bf16 v[80:83], v[182:185], v[206:209], v[80:83]
	s_setprio 3
	s_barrier
	v_mfma_f32_16x16x32_bf16 v[68:71], v[172:175], v[214:217], v[68:71]
	v_mfma_f32_16x16x32_bf16 v[64:67], v[182:185], v[214:217], v[64:67]
	s_setprio 0
	s_add_i32 s18, s46, s28
	v_lshl_add_u64 v[218:219], v[218:219], 0, s[12:13]
	s_mov_b32 m0, s18
	ds_read_b128 v[186:189], v153 offset:49152
	ds_read_b128 v[190:193], v153 offset:50176
	ds_read_b128 v[194:197], v153 offset:51200
	ds_read_b128 v[198:201], v153 offset:52224
	ds_read_b128 v[202:205], v153 offset:53248
	ds_read_b128 v[206:209], v153 offset:54272
	ds_read_b128 v[210:213], v153 offset:55296
	ds_read_b128 v[214:217], v153 offset:56320
	s_mov_b64 exec, s[98:99]
	global_load_lds_dwordx4 v[218:219], off
	s_add_i32 m0, s18, 0x2000
	s_add_u32 s18, s22, 0xb0080
	v_lshl_add_u64 v[218:219], v[220:221], 0, s[12:13]
	s_addc_u32 s19, s23, 0
	s_add_i32 s22, s47, s28
	global_load_lds_dwordx4 v[218:219], off
	v_lshl_add_u64 v[218:219], s[18:19], 0, v[130:131]
	s_mov_b32 m0, s22
	s_nop 0
	global_load_lds_dwordx4 v[218:219], off
	v_lshl_add_u64 v[218:219], s[18:19], 0, v[134:135]
	s_add_i32 m0, s22, 0x2000
	s_nop 0
	global_load_lds_dwordx4 v[218:219], off
	s_mov_b64 exec, -1
	s_cmp_lg_u32 s99, 0
	s_cbranch_scc1 .Lng_7_3
	s_waitcnt vmcnt(0)
.Lng_7_3:
	s_waitcnt vmcnt(6)
	s_waitcnt lgkmcnt(0)
	s_barrier
	s_waitcnt lgkmcnt(0)
	v_mfma_f32_16x16x32_bf16 v[60:63], v[144:147], v[186:189], v[60:63]
	v_mfma_f32_16x16x32_bf16 v[56:59], v[160:163], v[186:189], v[56:59]
	v_mfma_f32_16x16x32_bf16 v[44:47], v[144:147], v[194:197], v[44:47]
	v_mfma_f32_16x16x32_bf16 v[40:43], v[160:163], v[194:197], v[40:43]
	v_mfma_f32_16x16x32_bf16 v[28:31], v[144:147], v[202:205], v[28:31]
	v_mfma_f32_16x16x32_bf16 v[24:27], v[160:163], v[202:205], v[24:27]
	v_mfma_f32_16x16x32_bf16 v[12:15], v[144:147], v[210:213], v[12:15]
	v_mfma_f32_16x16x32_bf16 v[8:11], v[160:163], v[210:213], v[8:11]
	v_mfma_f32_16x16x32_bf16 v[60:63], v[156:159], v[190:193], v[60:63]
	v_mfma_f32_16x16x32_bf16 v[56:59], v[164:167], v[190:193], v[56:59]
	v_mfma_f32_16x16x32_bf16 v[44:47], v[156:159], v[198:201], v[44:47]
	v_mfma_f32_16x16x32_bf16 v[40:43], v[164:167], v[198:201], v[40:43]
	v_mfma_f32_16x16x32_bf16 v[28:31], v[156:159], v[206:209], v[28:31]
	v_mfma_f32_16x16x32_bf16 v[24:27], v[164:167], v[206:209], v[24:27]
	v_mfma_f32_16x16x32_bf16 v[12:15], v[156:159], v[214:217], v[12:15]
	v_mfma_f32_16x16x32_bf16 v[8:11], v[164:167], v[214:217], v[8:11]
	v_mfma_f32_16x16x32_bf16 v[52:55], v[168:171], v[186:189], v[52:55]
	v_mfma_f32_16x16x32_bf16 v[48:51], v[176:179], v[186:189], v[48:51]
	v_mfma_f32_16x16x32_bf16 v[36:39], v[168:171], v[194:197], v[36:39]
	v_mfma_f32_16x16x32_bf16 v[32:35], v[176:179], v[194:197], v[32:35]
	v_mfma_f32_16x16x32_bf16 v[20:23], v[168:171], v[202:205], v[20:23]
	v_mfma_f32_16x16x32_bf16 v[16:19], v[176:179], v[202:205], v[16:19]
	v_mfma_f32_16x16x32_bf16 v[4:7], v[168:171], v[210:213], v[4:7]
	v_mfma_f32_16x16x32_bf16 v[0:3], v[176:179], v[210:213], v[0:3]
	v_mfma_f32_16x16x32_bf16 v[52:55], v[172:175], v[190:193], v[52:55]
	v_mfma_f32_16x16x32_bf16 v[48:51], v[182:185], v[190:193], v[48:51]
	v_mfma_f32_16x16x32_bf16 v[36:39], v[172:175], v[198:201], v[36:39]
	v_mfma_f32_16x16x32_bf16 v[32:35], v[182:185], v[198:201], v[32:35]
	v_mfma_f32_16x16x32_bf16 v[20:23], v[172:175], v[206:209], v[20:23]
	v_mfma_f32_16x16x32_bf16 v[16:19], v[182:185], v[206:209], v[16:19]
	s_setprio 3
	s_barrier
	v_mfma_f32_16x16x32_bf16 v[4:7], v[172:175], v[214:217], v[4:7]
	v_mfma_f32_16x16x32_bf16 v[0:3], v[182:185], v[214:217], v[0:3]
	s_setprio 0
	v_lshl_add_u64 v[218:219], v[222:223], 0, s[12:13]
	s_mov_b32 m0, s35
	s_nop 0
	s_mov_b64 exec, s[98:99]
	global_load_lds_dwordx4 v[218:219], off
	v_lshl_add_u64 v[218:219], v[224:225], 0, s[12:13]
	s_mov_b32 m0, s36
	s_nop 0
	global_load_lds_dwordx4 v[218:219], off
	s_mov_b64 exec, -1
	s_add_i32 s45, s45, 2
	s_add_u32 s43, s43, 0x100
	s_addc_u32 s44, s44, 0
	s_cmp_gt_u32 s45, 41
	s_mov_b64 s[18:19], s[20:21]
	s_cbranch_scc0 .LBB0_1461
	s_and_b64 vcc, exec, s[14:15]
	s_cbranch_vccz .LBB0_1464
	s_barrier
